# f32 IEEE-division expansions -> v_rcp_f32*x and denorm-guarded rsqrt -> v_rsq_f32 in WY step1, gdn_norm, gate epilogue; pes loads batched
# speedup vs baseline: 1.0135x; 1.0116x over previous
; #define LAS __attribute__((address_space(3)))
; __device__ __forceinline__ void p3_sample_seq(const Ctx& c, int l, int b) {
;     ...
;     for (int i = c.tid; i < 2048; i += 512) *(LAS f32x4*)(PHI + 4 * i) = *(const f32x4*)(phi + 4 * i);
;     const int type = lane >> 5, d0 = (lane & 15) * 4;
;     f32x4 pes = (f32x4){0.f, 0.f, 0.f, 0.f};
; #pragma unroll 8
;     for (int i = 0; i < 32; ++i) pes += *(const f32x4*)(pe + (type * 32 + i) * 64 + d0);
;     __syncthreads();
;     int pgs = 0; if (lane < 8) pgs = ptab[b * NPG + ((wid + 8 * lane) >> 2)];
.LBB0_719:
	global_load_dwordx4 v[144:147], v[12:13], off
	global_load_dwordx4 v[148:151], v[12:13], off offset:256
	global_load_dwordx4 v[152:155], v[12:13], off offset:512
	global_load_dwordx4 v[156:159], v[12:13], off offset:768
	global_load_dwordx4 v[160:163], v[12:13], off offset:1024
	global_load_dwordx4 v[164:167], v[12:13], off offset:1280
	global_load_dwordx4 v[168:171], v[12:13], off offset:1536
	global_load_dwordx4 v[172:175], v[12:13], off offset:1792
	global_load_dwordx4 v[176:179], v[12:13], off offset:2048
	global_load_dwordx4 v[180:183], v[12:13], off offset:2304
	global_load_dwordx4 v[184:187], v[12:13], off offset:2560
	global_load_dwordx4 v[190:193], v[12:13], off offset:2816
	global_load_dwordx4 v[194:197], v[12:13], off offset:3072
	global_load_dwordx4 v[198:201], v[12:13], off offset:3328
	global_load_dwordx4 v[202:205], v[12:13], off offset:3584
	global_load_dwordx4 v[206:209], v[12:13], off offset:3840
	v_add_co_u32_e32 v14, vcc, 0x1000, v12
	s_nop 1
	v_addc_co_u32_e32 v15, vcc, 0, v13, vcc
	global_load_dwordx4 v[210:213], v[14:15], off
	global_load_dwordx4 v[214:217], v[14:15], off offset:256
	global_load_dwordx4 v[98:101], v[14:15], off offset:512
	global_load_dwordx4 v[102:105], v[14:15], off offset:768
	global_load_dwordx4 v[106:109], v[14:15], off offset:1024
	global_load_dwordx4 v[110:113], v[14:15], off offset:1280
	global_load_dwordx4 v[114:117], v[14:15], off offset:1536
	global_load_dwordx4 v[118:121], v[14:15], off offset:1792
	global_load_dwordx4 v[122:125], v[14:15], off offset:2048
	global_load_dwordx4 v[30:33], v[14:15], off offset:2304
	global_load_dwordx4 v[34:37], v[14:15], off offset:2560
	global_load_dwordx4 v[38:41], v[14:15], off offset:2816
	global_load_dwordx4 v[42:45], v[14:15], off offset:3072
	global_load_dwordx4 v[230:233], v[14:15], off offset:3328
	global_load_dwordx4 v[234:237], v[14:15], off offset:3584
	global_load_dwordx4 v[238:241], v[14:15], off offset:3840
	s_waitcnt vmcnt(31)
	v_pk_add_f32 v[2:3], v[2:3], v[144:145]
	v_pk_add_f32 v[4:5], v[4:5], v[146:147]
	s_waitcnt vmcnt(30)
	v_pk_add_f32 v[2:3], v[2:3], v[148:149]
	v_pk_add_f32 v[4:5], v[4:5], v[150:151]
	s_waitcnt vmcnt(29)
	v_pk_add_f32 v[2:3], v[2:3], v[152:153]
	v_pk_add_f32 v[4:5], v[4:5], v[154:155]
	s_waitcnt vmcnt(28)
	v_pk_add_f32 v[2:3], v[2:3], v[156:157]
	v_pk_add_f32 v[4:5], v[4:5], v[158:159]
	s_waitcnt vmcnt(27)
	v_pk_add_f32 v[2:3], v[2:3], v[160:161]
	v_pk_add_f32 v[4:5], v[4:5], v[162:163]
	s_waitcnt vmcnt(26)
	v_pk_add_f32 v[2:3], v[2:3], v[164:165]
	v_pk_add_f32 v[4:5], v[4:5], v[166:167]
	s_waitcnt vmcnt(25)
	v_pk_add_f32 v[2:3], v[2:3], v[168:169]
	v_pk_add_f32 v[4:5], v[4:5], v[170:171]
	s_waitcnt vmcnt(24)
	v_pk_add_f32 v[2:3], v[2:3], v[172:173]
	v_pk_add_f32 v[4:5], v[4:5], v[174:175]
	s_waitcnt vmcnt(23)
	v_pk_add_f32 v[2:3], v[2:3], v[176:177]
	v_pk_add_f32 v[4:5], v[4:5], v[178:179]
	s_waitcnt vmcnt(22)
	v_pk_add_f32 v[2:3], v[2:3], v[180:181]
	v_pk_add_f32 v[4:5], v[4:5], v[182:183]
	s_waitcnt vmcnt(21)
	v_pk_add_f32 v[2:3], v[2:3], v[184:185]
	v_pk_add_f32 v[4:5], v[4:5], v[186:187]
	s_waitcnt vmcnt(20)
	v_pk_add_f32 v[2:3], v[2:3], v[190:191]
	v_pk_add_f32 v[4:5], v[4:5], v[192:193]
	s_waitcnt vmcnt(19)
	v_pk_add_f32 v[2:3], v[2:3], v[194:195]
	v_pk_add_f32 v[4:5], v[4:5], v[196:197]
	s_waitcnt vmcnt(18)
	v_pk_add_f32 v[2:3], v[2:3], v[198:199]
	v_pk_add_f32 v[4:5], v[4:5], v[200:201]
	s_waitcnt vmcnt(17)
	v_pk_add_f32 v[2:3], v[2:3], v[202:203]
	v_pk_add_f32 v[4:5], v[4:5], v[204:205]
	s_waitcnt vmcnt(16)
	v_pk_add_f32 v[2:3], v[2:3], v[206:207]
	v_pk_add_f32 v[4:5], v[4:5], v[208:209]
	s_waitcnt vmcnt(15)
	v_pk_add_f32 v[2:3], v[2:3], v[210:211]
	v_pk_add_f32 v[4:5], v[4:5], v[212:213]
	s_waitcnt vmcnt(14)
	v_pk_add_f32 v[2:3], v[2:3], v[214:215]
	v_pk_add_f32 v[4:5], v[4:5], v[216:217]
	s_waitcnt vmcnt(13)
	v_pk_add_f32 v[2:3], v[2:3], v[98:99]
	v_pk_add_f32 v[4:5], v[4:5], v[100:101]
	s_waitcnt vmcnt(12)
	v_pk_add_f32 v[2:3], v[2:3], v[102:103]
	v_pk_add_f32 v[4:5], v[4:5], v[104:105]
	s_waitcnt vmcnt(11)
	v_pk_add_f32 v[2:3], v[2:3], v[106:107]
	v_pk_add_f32 v[4:5], v[4:5], v[108:109]
	s_waitcnt vmcnt(10)
	v_pk_add_f32 v[2:3], v[2:3], v[110:111]
	v_pk_add_f32 v[4:5], v[4:5], v[112:113]
	s_waitcnt vmcnt(9)
	v_pk_add_f32 v[2:3], v[2:3], v[114:115]
	v_pk_add_f32 v[4:5], v[4:5], v[116:117]
	s_waitcnt vmcnt(8)
	v_pk_add_f32 v[2:3], v[2:3], v[118:119]
	v_pk_add_f32 v[4:5], v[4:5], v[120:121]
	s_waitcnt vmcnt(7)
	v_pk_add_f32 v[2:3], v[2:3], v[122:123]
	v_pk_add_f32 v[4:5], v[4:5], v[124:125]
	s_waitcnt vmcnt(6)
	v_pk_add_f32 v[2:3], v[2:3], v[30:31]
	v_pk_add_f32 v[4:5], v[4:5], v[32:33]
	s_waitcnt vmcnt(5)
	v_pk_add_f32 v[2:3], v[2:3], v[34:35]
	v_pk_add_f32 v[4:5], v[4:5], v[36:37]
	s_waitcnt vmcnt(4)
	v_pk_add_f32 v[2:3], v[2:3], v[38:39]
	v_pk_add_f32 v[4:5], v[4:5], v[40:41]
	s_waitcnt vmcnt(3)
	v_pk_add_f32 v[2:3], v[2:3], v[42:43]
	v_pk_add_f32 v[4:5], v[4:5], v[44:45]
	s_waitcnt vmcnt(2)
	v_pk_add_f32 v[2:3], v[2:3], v[230:231]
	v_pk_add_f32 v[4:5], v[4:5], v[232:233]
	s_waitcnt vmcnt(1)
	v_pk_add_f32 v[2:3], v[2:3], v[234:235]
	v_pk_add_f32 v[4:5], v[4:5], v[236:237]
	s_waitcnt vmcnt(0)
	v_pk_add_f32 v[2:3], v[2:3], v[238:239]
	v_pk_add_f32 v[4:5], v[4:5], v[240:241]
	v_mov_b32_e32 v30, 0
	s_waitcnt lgkmcnt(0)
	s_barrier
	s_and_saveexec_b64 s[2:3], s[42:43]
	s_cbranch_execz .LBB0_722
	v_lshl_add_u32 v14, s0, 4, v16
	v_mov_b32_e32 v12, s17
	v_mov_b32_e32 v13, s18
	v_ashrrev_i32_e32 v15, 31, v14
	v_lshl_add_u64 v[12:13], v[14:15], 2, v[12:13]
	global_load_dword v30, v[12:13], off

; #define LAS __attribute__((address_space(3)))
; __device__ __forceinline__ float bf2f(bf16 v) { return __uint_as_float(((unsigned)v) << 16); }
; __device__ __forceinline__ unsigned f2bf(float f) { unsigned u = __float_as_uint(f); return (u + 0x7fffu + ((u >> 16) & 1u)) >> 16; }
; __device__ __forceinline__ float siluf_(float x) { return x / (1.0f + __expf(-x)); }
; __device__ __forceinline__ int wy_producer_task(const Ctx& c, int l, int tk, WyPre& P, unsigned* head) {
;     ...
;     for (int j = 0; j < 3; ++j) { float xv[11];
; #pragma unroll
;         for (int r = 0; r < 11; ++r) xv[r] = bf2f((bf16)P.hx[j][r]);
; #pragma unroll
;         for (int r = 0; r < 8; ++r) { const int i = 8 * wid + r;
;             float y = siluf_(P.cw[j][0] * xv[r] + P.cw[j][1] * xv[r + 1] + P.cw[j][2] * xv[r + 2] + P.cw[j][3] * xv[r + 3]);
;             if (j < 2) y *= rsqrtf(wave_sum_fast(y * y) + RMS_EPS) * (j == 0 ? 0.125f : 1.0f);
;             if (j == 0) QF[i * 65 + lane] = y;
;             else if (j == 1) { KF[i * 65 + lane] = y; *(LAS bf16*)(KIMG + (lane >> 3) * 1024 + i * 16 + (lane & 7) * 2) = (bf16)f2bf(y); }
;             else VF[i * 65 + lane] = y; } }
.LBB0_964:
	s_or_b64 exec, exec, s[2:3]
	v_lshlrev_b32_e32 v6, 16, v114
	v_and_b32_e32 v7, 0xffff0000, v114
	v_pk_mul_f32 v[8:9], v[84:85], v[6:7]
	v_and_b32_e32 v11, 0xffff0000, v89
	v_lshlrev_b32_e32 v10, 16, v89
	v_pk_mul_f32 v[12:13], v[86:87], v[10:11]
	v_add_f32_e32 v7, v8, v9
	v_add_f32_e32 v7, v13, v7
	v_add_f32_e32 v7, v12, v7
	v_mul_f32_e32 v8, 0xbfb8aa3b, v7
	v_exp_f32_e32 v8, v8
	v_lshlrev_b32_e32 v2, 2, v88
	s_add_i32 s1, 0, 0x11d00
	v_add_u32_e32 v3, 0, v2
	v_add_f32_e32 v8, 1.0, v8
	v_rcp_f32_e32 v9, v8
	v_add_u32_e32 v4, s1, v2
	v_lshlrev_b32_e32 v2, 7, v88
	v_lshlrev_b32_e32 v5, 1, v88
	s_nop 0
	v_mul_f32_e32 v7, v7, v9
	v_mul_f32_e32 v8, v7, v7
	v_and_b32_e32 v2, 0xfffffc00, v2
	v_and_b32_e32 v5, 14, v5
	v_mov_b32_dpp v8, v8 quad_perm:[1,0,3,2] row_mask:0xf bank_mask:0xf bound_ctrl:1
	v_fmac_f32_e32 v8, v7, v7
	v_readlane_b32 s1, v254, 32
	s_mov_b32 s7, 0x800000
	v_add_f32_dpp v8, v8, v8 quad_perm:[2,3,0,1] row_mask:0xf bank_mask:0xf bound_ctrl:1
	v_add3_u32 v5, s1, v2, v5
	v_and_b32_e32 v17, 0xffff0000, v115
	v_add_f32_dpp v8, v8, v8 row_half_mirror row_mask:0xf bank_mask:0xf bound_ctrl:1
	v_lshlrev_b32_e32 v16, 16, v115
	v_pk_mul_f32 v[14:15], v[84:85], v[10:11]
	v_add_f32_dpp v8, v8, v8 row_mirror row_mask:0xf bank_mask:0xf bound_ctrl:1
	v_lshlrev_b32_e32 v2, 16, v94
	v_readlane_b32 s1, v8, 16
	v_readlane_b32 s6, v8, 48
	v_readlane_b32 s2, v8, 0
	v_readlane_b32 s3, v8, 32
	v_mov_b32_e32 v8, s1
	v_mov_b32_e32 v9, s6
	v_pk_add_f32 v[8:9], s[2:3], v[8:9]
	s_nop 0
	v_add_f32_e32 v8, v8, v9
	v_add_f32_e32 v8, 0x358637bd, v8
	s_nop 0
	v_rsq_f32_e32 v8, v8
	s_nop 0
	v_mul_f32_e32 v8, 0x3e000000, v8
	v_mul_f32_e32 v7, v7, v8
	v_pk_mov_b32 v[12:13], v[10:11], v[6:7] op_sel:[1,0]
	v_pk_mov_b32 v[10:11], v[16:17], v[10:11] op_sel:[1,0]
	v_pk_mul_f32 v[12:13], v[84:85], v[12:13]
	v_add_u32_e32 v8, s96, v3
	v_add_u32_e32 v6, s97, v3
	v_pk_mul_f32 v[18:19], v[86:87], v[10:11]
	v_add_f32_e32 v3, v12, v13
	v_add_f32_e32 v3, v19, v3
	v_add_f32_e32 v3, v18, v3
	v_mul_f32_e32 v9, 0xbfb8aa3b, v3
	v_exp_f32_e32 v9, v9
	v_pk_mul_f32 v[10:11], v[84:85], v[10:11]
	v_add_f32_e32 v9, 1.0, v9
	v_rcp_f32_e32 v12, v9
	s_nop 0
	s_nop 0
	v_mul_f32_e32 v3, v3, v12
	v_mul_f32_e32 v9, v3, v3
	s_nop 1
	v_mov_b32_dpp v9, v9 quad_perm:[1,0,3,2] row_mask:0xf bank_mask:0xf bound_ctrl:1
	v_fmac_f32_e32 v9, v3, v3
	s_nop 1
	v_add_f32_dpp v9, v9, v9 quad_perm:[2,3,0,1] row_mask:0xf bank_mask:0xf bound_ctrl:1
	s_nop 1
	v_add_f32_dpp v9, v9, v9 row_half_mirror row_mask:0xf bank_mask:0xf bound_ctrl:1
	s_nop 1
	v_add_f32_dpp v9, v9, v9 row_mirror row_mask:0xf bank_mask:0xf bound_ctrl:1
	s_nop 0
	v_readlane_b32 s1, v9, 16
	v_readlane_b32 s6, v9, 48
	v_readlane_b32 s2, v9, 0
	v_readlane_b32 s3, v9, 32
	v_mov_b32_e32 v12, s1
	v_mov_b32_e32 v13, s6
	v_pk_add_f32 v[12:13], s[2:3], v[12:13]
	s_nop 0
	v_add_f32_e32 v9, v12, v13
	v_add_f32_e32 v9, 0x358637bd, v9
	s_nop 0
	v_rsq_f32_e32 v9, v9
	s_nop 0
	v_mul_f32_e32 v9, 0x3e000000, v9
	v_mul_f32_e32 v3, v3, v9
	v_pk_mul_f32 v[12:13], v[86:87], v[16:17]
	v_add_f32_e32 v9, v14, v15
	v_add_f32_e32 v9, v13, v9
	v_add_f32_e32 v9, v12, v9
	v_mul_f32_e32 v12, 0xbfb8aa3b, v9
	v_exp_f32_e32 v12, v12
	s_nop 0
	v_add_f32_e32 v12, 1.0, v12
	v_rcp_f32_e32 v13, v12
	s_nop 0
	s_nop 0
	v_mul_f32_e32 v9, v9, v13
	v_mul_f32_e32 v12, v9, v9
	v_and_b32_e32 v15, 0xffff0000, v116
	v_lshlrev_b32_e32 v14, 16, v116
	v_mov_b32_dpp v12, v12 quad_perm:[1,0,3,2] row_mask:0xf bank_mask:0xf bound_ctrl:1
	v_fmac_f32_e32 v12, v9, v9
	s_nop 1
	v_add_f32_dpp v12, v12, v12 quad_perm:[2,3,0,1] row_mask:0xf bank_mask:0xf bound_ctrl:1
	s_nop 1
	v_add_f32_dpp v12, v12, v12 row_half_mirror row_mask:0xf bank_mask:0xf bound_ctrl:1
	s_nop 1
	v_add_f32_dpp v12, v12, v12 row_mirror row_mask:0xf bank_mask:0xf bound_ctrl:1
	s_nop 0
	v_readlane_b32 s1, v12, 16
	v_readlane_b32 s6, v12, 48
	v_readlane_b32 s2, v12, 0
	v_readlane_b32 s3, v12, 32
	v_mov_b32_e32 v12, s1
	v_mov_b32_e32 v13, s6
	v_pk_add_f32 v[12:13], s[2:3], v[12:13]
	s_nop 0
	v_add_f32_e32 v12, v12, v13
	v_add_f32_e32 v12, 0x358637bd, v12
	s_nop 0
	v_rsq_f32_e32 v12, v12
	s_nop 0
	v_mul_f32_e32 v12, 0x3e000000, v12
	v_mul_f32_e32 v9, v9, v12
	v_add_u32_e32 v12, 0x4400, v6
	ds_write2_b32 v12, v3, v9 offset0:64 offset1:129
	v_pk_mul_f32 v[12:13], v[84:85], v[16:17]
	v_pk_mov_b32 v[16:17], v[14:15], v[16:17] op_sel:[1,0]
	v_add_f32_e32 v3, v10, v11
	v_pk_mul_f32 v[18:19], v[86:87], v[16:17]
	s_nop 0
	v_add_f32_e32 v3, v19, v3
	v_add_f32_e32 v3, v18, v3
	v_mul_f32_e32 v9, 0xbfb8aa3b, v3
	v_exp_f32_e32 v9, v9
	s_nop 0
	v_add_f32_e32 v9, 1.0, v9
	v_rcp_f32_e32 v10, v9
	s_nop 0
	s_nop 0
	v_mul_f32_e32 v3, v3, v10
	v_mul_f32_e32 v9, v3, v3
	s_nop 1
	v_mov_b32_dpp v9, v9 quad_perm:[1,0,3,2] row_mask:0xf bank_mask:0xf bound_ctrl:1
	v_fmac_f32_e32 v9, v3, v3
	s_nop 1
	v_add_f32_dpp v9, v9, v9 quad_perm:[2,3,0,1] row_mask:0xf bank_mask:0xf bound_ctrl:1
	s_nop 1
	v_add_f32_dpp v9, v9, v9 row_half_mirror row_mask:0xf bank_mask:0xf bound_ctrl:1
	s_nop 1
	v_add_f32_dpp v9, v9, v9 row_mirror row_mask:0xf bank_mask:0xf bound_ctrl:1
	s_nop 0
	v_readlane_b32 s1, v9, 16
	v_readlane_b32 s6, v9, 48
	v_readlane_b32 s2, v9, 0
	v_readlane_b32 s3, v9, 32
	v_mov_b32_e32 v10, s1
	v_mov_b32_e32 v11, s6
	v_pk_add_f32 v[10:11], s[2:3], v[10:11]
	s_nop 0
	v_add_f32_e32 v9, v10, v11
	v_add_f32_e32 v9, 0x358637bd, v9
	s_nop 0
	v_rsq_f32_e32 v9, v9
	s_nop 0
	v_mul_f32_e32 v9, 0x3e000000, v9
	v_mul_f32_e32 v3, v3, v9
	v_pk_mul_f32 v[10:11], v[86:87], v[14:15]
	v_add_f32_e32 v9, v12, v13
	v_add_f32_e32 v9, v11, v9
	v_add_f32_e32 v9, v10, v9
	v_mul_f32_e32 v10, 0xbfb8aa3b, v9
	v_exp_f32_e32 v10, v10
	s_nop 0
	v_add_f32_e32 v10, 1.0, v10
; #define LAS __attribute__((address_space(3)))
; __device__ __forceinline__ float bf2f(bf16 v) { return __uint_as_float(((unsigned)v) << 16); }
; __device__ __forceinline__ unsigned f2bf(float f) { unsigned u = __float_as_uint(f); return (u + 0x7fffu + ((u >> 16) & 1u)) >> 16; }
; __device__ __forceinline__ float siluf_(float x) { return x / (1.0f + __expf(-x)); }
; __device__ __forceinline__ int wy_producer_task(const Ctx& c, int l, int tk, WyPre& P, unsigned* head) {
;     ...
;     for (int j = 0; j < 3; ++j) { float xv[11];
; #pragma unroll
;         for (int r = 0; r < 11; ++r) xv[r] = bf2f((bf16)P.hx[j][r]);
; #pragma unroll
;         for (int r = 0; r < 8; ++r) { const int i = 8 * wid + r;
;             float y = siluf_(P.cw[j][0] * xv[r] + P.cw[j][1] * xv[r + 1] + P.cw[j][2] * xv[r + 2] + P.cw[j][3] * xv[r + 3]);
;             if (j < 2) y *= rsqrtf(wave_sum_fast(y * y) + RMS_EPS) * (j == 0 ? 0.125f : 1.0f);
;             if (j == 0) QF[i * 65 + lane] = y;
;             else if (j == 1) { KF[i * 65 + lane] = y; *(LAS bf16*)(KIMG + (lane >> 3) * 1024 + i * 16 + (lane & 7) * 2) = (bf16)f2bf(y); }
;             else VF[i * 65 + lane] = y; } }
	v_rcp_f32_e32 v11, v10
	s_nop 0
	s_nop 0
	v_mul_f32_e32 v9, v9, v11
	v_mul_f32_e32 v10, v9, v9
	v_pk_mul_f32 v[12:13], v[84:85], v[14:15]
	s_nop 0
	v_mov_b32_dpp v10, v10 quad_perm:[1,0,3,2] row_mask:0xf bank_mask:0xf bound_ctrl:1
	v_fmac_f32_e32 v10, v9, v9
	s_nop 1
	v_add_f32_dpp v10, v10, v10 quad_perm:[2,3,0,1] row_mask:0xf bank_mask:0xf bound_ctrl:1
	s_nop 1
	v_add_f32_dpp v10, v10, v10 row_half_mirror row_mask:0xf bank_mask:0xf bound_ctrl:1
	s_nop 1
	v_add_f32_dpp v10, v10, v10 row_mirror row_mask:0xf bank_mask:0xf bound_ctrl:1
	s_nop 0
	v_readlane_b32 s1, v10, 16
	v_readlane_b32 s6, v10, 48
	v_readlane_b32 s2, v10, 0
	v_readlane_b32 s3, v10, 32
	v_mov_b32_e32 v10, s1
	v_mov_b32_e32 v11, s6
	v_pk_add_f32 v[10:11], s[2:3], v[10:11]
	s_nop 0
	v_add_f32_e32 v10, v10, v11
	v_add_f32_e32 v10, 0x358637bd, v10
	s_nop 0
	v_rsq_f32_e32 v10, v10
	s_nop 0
	v_mul_f32_e32 v10, 0x3e000000, v10
	v_mul_f32_e32 v9, v9, v10
	v_add_u32_e32 v10, 0x4600, v6
	ds_write2_b32 v10, v3, v9 offset0:66 offset1:131
	v_pk_mul_f32 v[10:11], v[84:85], v[16:17]
	v_and_b32_e32 v17, 0xffff0000, v117
	v_lshlrev_b32_e32 v16, 16, v117
	v_pk_mov_b32 v[14:15], v[16:17], v[14:15] op_sel:[1,0]
	v_add_f32_e32 v3, v10, v11
	v_pk_mul_f32 v[18:19], v[86:87], v[14:15]
	s_nop 0
	v_add_f32_e32 v3, v19, v3
	v_add_f32_e32 v3, v18, v3
	v_mul_f32_e32 v9, 0xbfb8aa3b, v3
	v_exp_f32_e32 v9, v9
	s_nop 0
	v_add_f32_e32 v9, 1.0, v9
	v_rcp_f32_e32 v10, v9
	s_nop 0
	s_nop 0
	v_mul_f32_e32 v3, v3, v10
	v_mul_f32_e32 v9, v3, v3
	s_nop 1
	v_mov_b32_dpp v9, v9 quad_perm:[1,0,3,2] row_mask:0xf bank_mask:0xf bound_ctrl:1
	v_fmac_f32_e32 v9, v3, v3
	s_nop 1
	v_add_f32_dpp v9, v9, v9 quad_perm:[2,3,0,1] row_mask:0xf bank_mask:0xf bound_ctrl:1
	s_nop 1
	v_add_f32_dpp v9, v9, v9 row_half_mirror row_mask:0xf bank_mask:0xf bound_ctrl:1
	s_nop 1
	v_add_f32_dpp v9, v9, v9 row_mirror row_mask:0xf bank_mask:0xf bound_ctrl:1
	s_nop 0
	v_readlane_b32 s1, v9, 16
	v_readlane_b32 s6, v9, 48
	v_readlane_b32 s2, v9, 0
	v_readlane_b32 s3, v9, 32
	v_mov_b32_e32 v10, s1
	v_mov_b32_e32 v11, s6
	v_pk_add_f32 v[10:11], s[2:3], v[10:11]
	s_nop 0
	v_add_f32_e32 v9, v10, v11
	v_add_f32_e32 v9, 0x358637bd, v9
	s_nop 0
	v_rsq_f32_e32 v9, v9
	s_nop 0
	v_mul_f32_e32 v9, 0x3e000000, v9
	v_mul_f32_e32 v3, v3, v9
	v_pk_mul_f32 v[10:11], v[86:87], v[16:17]
	v_add_f32_e32 v9, v12, v13
	v_add_f32_e32 v9, v11, v9
	v_add_f32_e32 v9, v10, v9
	v_mul_f32_e32 v10, 0xbfb8aa3b, v9
	v_exp_f32_e32 v10, v10
	s_nop 0
	v_add_f32_e32 v10, 1.0, v10
	v_rcp_f32_e32 v11, v10
	s_nop 0
	s_nop 0
	v_mul_f32_e32 v9, v9, v11
	v_mul_f32_e32 v10, v9, v9
	s_nop 1
	v_mov_b32_dpp v10, v10 quad_perm:[1,0,3,2] row_mask:0xf bank_mask:0xf bound_ctrl:1
	v_fmac_f32_e32 v10, v9, v9
	s_nop 1
	v_add_f32_dpp v10, v10, v10 quad_perm:[2,3,0,1] row_mask:0xf bank_mask:0xf bound_ctrl:1
	s_nop 1
	v_add_f32_dpp v10, v10, v10 row_half_mirror row_mask:0xf bank_mask:0xf bound_ctrl:1
	s_nop 1
	v_add_f32_dpp v10, v10, v10 row_mirror row_mask:0xf bank_mask:0xf bound_ctrl:1
	s_nop 0
	v_readlane_b32 s1, v10, 16
	v_readlane_b32 s6, v10, 48
	v_readlane_b32 s2, v10, 0
	v_readlane_b32 s3, v10, 32
	v_mov_b32_e32 v10, s1
	v_mov_b32_e32 v11, s6
	v_pk_add_f32 v[10:11], s[2:3], v[10:11]
	s_nop 0
	v_add_f32_e32 v10, v10, v11
	v_add_f32_e32 v10, 0x358637bd, v10
	s_nop 0
	v_rsq_f32_e32 v10, v10
	s_nop 0
	v_mul_f32_e32 v10, 0x3e000000, v10
	v_mul_f32_e32 v9, v9, v10
	v_add_u32_e32 v10, 0x4800, v6
	ds_write2_b32 v10, v3, v9 offset0:68 offset1:133
	v_pk_mul_f32 v[10:11], v[84:85], v[14:15]
	v_mov_b32_e32 v3, v16
	v_pk_mul_f32 v[2:3], v[86:87], v[2:3]
	v_add_f32_e32 v9, v10, v11
	v_add_f32_e32 v3, v3, v9
	v_add_f32_e32 v2, v2, v3
	v_mul_f32_e32 v3, 0xbfb8aa3b, v2
	v_exp_f32_e32 v3, v3
	v_and_b32_e32 v15, 0xffff0000, v118
	v_lshlrev_b32_e32 v14, 16, v118
	s_waitcnt vmcnt(4)
	v_pk_mul_f32 v[16:17], v[92:93], v[14:15]
	v_add_f32_e32 v3, 1.0, v3
	v_rcp_f32_e32 v9, v3
	s_nop 0
	s_nop 0
	v_mul_f32_e32 v9, v2, v9
	v_mul_f32_e32 v2, v9, v9
	v_lshlrev_b32_e32 v10, 16, v119
	v_and_b32_e32 v11, 0xffff0000, v119
	v_mov_b32_dpp v2, v2 quad_perm:[1,0,3,2] row_mask:0xf bank_mask:0xf bound_ctrl:1
	v_fmac_f32_e32 v2, v9, v9
	v_pk_mul_f32 v[12:13], v[90:91], v[10:11]
	s_nop 0
	v_add_f32_dpp v2, v2, v2 quad_perm:[2,3,0,1] row_mask:0xf bank_mask:0xf bound_ctrl:1
	s_nop 1
	v_add_f32_dpp v2, v2, v2 row_half_mirror row_mask:0xf bank_mask:0xf bound_ctrl:1
	s_nop 1
	v_add_f32_dpp v2, v2, v2 row_mirror row_mask:0xf bank_mask:0xf bound_ctrl:1
	s_nop 0
	v_readlane_b32 s1, v2, 16
	v_readlane_b32 s6, v2, 48
	v_readlane_b32 s2, v2, 0
	v_readlane_b32 s3, v2, 32
	v_mov_b32_e32 v2, s1
	v_mov_b32_e32 v3, s6
	v_pk_add_f32 v[2:3], s[2:3], v[2:3]
	s_nop 0
	v_add_f32_e32 v2, v2, v3
	v_add_f32_e32 v2, 0x358637bd, v2
	s_nop 0
	v_rsq_f32_e32 v2, v2
	s_nop 0
	v_add_f32_e32 v3, v12, v13
	v_add_f32_e32 v3, v17, v3
	v_mul_f32_e32 v2, 0x3e000000, v2
	v_add_f32_e32 v3, v16, v3
	v_mul_f32_e32 v2, v9, v2
	v_mul_f32_e32 v9, 0xbfb8aa3b, v3
	v_exp_f32_e32 v9, v9
	ds_write_b32 v6, v2 offset:19224
	v_lshlrev_b32_e32 v2, 16, v96
	v_add_f32_e32 v9, 1.0, v9
	v_rcp_f32_e32 v11, v9
	s_nop 0
	s_nop 0
	v_mul_f32_e32 v3, v3, v11
	v_mul_f32_e32 v9, v3, v3
	s_nop 1
	v_mov_b32_dpp v9, v9 quad_perm:[1,0,3,2] row_mask:0xf bank_mask:0xf bound_ctrl:1
	v_fmac_f32_e32 v9, v3, v3
	s_nop 1
	v_add_f32_dpp v9, v9, v9 quad_perm:[2,3,0,1] row_mask:0xf bank_mask:0xf bound_ctrl:1
	s_nop 1
	v_add_f32_dpp v9, v9, v9 row_half_mirror row_mask:0xf bank_mask:0xf bound_ctrl:1
	s_nop 1
	v_add_f32_dpp v9, v9, v9 row_mirror row_mask:0xf bank_mask:0xf bound_ctrl:1
	s_nop 0
	v_readlane_b32 s1, v9, 16
	v_readlane_b32 s6, v9, 48
	v_readlane_b32 s2, v9, 0
	v_readlane_b32 s3, v9, 32
; #define LAS __attribute__((address_space(3)))
; __device__ __forceinline__ float bf2f(bf16 v) { return __uint_as_float(((unsigned)v) << 16); }
; __device__ __forceinline__ unsigned f2bf(float f) { unsigned u = __float_as_uint(f); return (u + 0x7fffu + ((u >> 16) & 1u)) >> 16; }
; __device__ __forceinline__ float siluf_(float x) { return x / (1.0f + __expf(-x)); }
; __device__ __forceinline__ int wy_producer_task(const Ctx& c, int l, int tk, WyPre& P, unsigned* head) {
;     ...
;     for (int j = 0; j < 3; ++j) { float xv[11];
; #pragma unroll
;         for (int r = 0; r < 11; ++r) xv[r] = bf2f((bf16)P.hx[j][r]);
; #pragma unroll
;         for (int r = 0; r < 8; ++r) { const int i = 8 * wid + r;
;             float y = siluf_(P.cw[j][0] * xv[r] + P.cw[j][1] * xv[r + 1] + P.cw[j][2] * xv[r + 2] + P.cw[j][3] * xv[r + 3]);
;             if (j < 2) y *= rsqrtf(wave_sum_fast(y * y) + RMS_EPS) * (j == 0 ? 0.125f : 1.0f);
;             if (j == 0) QF[i * 65 + lane] = y;
;             else if (j == 1) { KF[i * 65 + lane] = y; *(LAS bf16*)(KIMG + (lane >> 3) * 1024 + i * 16 + (lane & 7) * 2) = (bf16)f2bf(y); }
;             else VF[i * 65 + lane] = y; } }
	v_mov_b32_e32 v12, s1
	v_mov_b32_e32 v13, s6
	v_pk_add_f32 v[12:13], s[2:3], v[12:13]
	s_nop 0
	v_add_f32_e32 v9, v12, v13
	v_add_f32_e32 v9, 0x358637bd, v9
	v_and_b32_e32 v13, 0xffff0000, v120
	v_rsq_f32_e32 v9, v9
	v_lshlrev_b32_e32 v12, 16, v120
	v_mul_f32_e32 v3, v3, v9
	ds_write2st64_b32 v8, v3, v7 offset0:4 offset1:69
	v_bfe_u32 v7, v3, 16, 1
	v_pk_mov_b32 v[8:9], v[14:15], v[10:11] op_sel:[1,0]
	v_add3_u32 v3, v3, v7, s15
	v_add_u32_e32 v7, s88, v5
	v_pk_mul_f32 v[8:9], v[90:91], v[8:9]
	v_pk_mul_f32 v[10:11], v[90:91], v[14:15]
	v_pk_mov_b32 v[14:15], v[12:13], v[14:15] op_sel:[1,0]
	ds_write_b16_d16_hi v7, v3
	v_pk_mul_f32 v[16:17], v[92:93], v[14:15]
	v_add_f32_e32 v7, v8, v9
	v_add_f32_e32 v7, v17, v7
	v_add_f32_e32 v7, v16, v7
	v_mul_f32_e32 v8, 0xbfb8aa3b, v7
	v_exp_f32_e32 v8, v8
	v_add_u32_e32 v3, s60, v5
	v_add_f32_e32 v8, 1.0, v8
	v_rcp_f32_e32 v9, v8
	s_nop 0
	s_nop 0
	v_mul_f32_e32 v7, v7, v9
	v_mul_f32_e32 v8, v7, v7
	v_add_u32_e32 v18, 0x400, v6
	s_nop 0
	v_mov_b32_dpp v8, v8 quad_perm:[1,0,3,2] row_mask:0xf bank_mask:0xf bound_ctrl:1
	v_fmac_f32_e32 v8, v7, v7
	s_nop 1
	v_add_f32_dpp v8, v8, v8 quad_perm:[2,3,0,1] row_mask:0xf bank_mask:0xf bound_ctrl:1
	s_nop 1
	v_add_f32_dpp v8, v8, v8 row_half_mirror row_mask:0xf bank_mask:0xf bound_ctrl:1
	s_nop 1
	v_add_f32_dpp v8, v8, v8 row_mirror row_mask:0xf bank_mask:0xf bound_ctrl:1
	s_nop 0
	v_readlane_b32 s1, v8, 16
	v_readlane_b32 s6, v8, 48
	v_readlane_b32 s2, v8, 0
	v_readlane_b32 s3, v8, 32
	v_mov_b32_e32 v8, s1
	v_mov_b32_e32 v9, s6
	v_pk_add_f32 v[8:9], s[2:3], v[8:9]
	s_nop 0
	v_add_f32_e32 v8, v8, v9
	v_add_f32_e32 v8, 0x358637bd, v8
	s_nop 0
	v_rsq_f32_e32 v8, v8
	s_nop 0
	v_mul_f32_e32 v7, v7, v8
	v_bfe_u32 v8, v7, 16, 1
	v_add3_u32 v8, v7, v8, s15
	ds_write_b16_d16_hi v3, v8
	v_pk_mul_f32 v[8:9], v[92:93], v[12:13]
	v_add_f32_e32 v3, v10, v11
	v_add_f32_e32 v3, v9, v3
	v_add_f32_e32 v3, v8, v3
	v_mul_f32_e32 v8, 0xbfb8aa3b, v3
	v_exp_f32_e32 v8, v8
	s_nop 0
	v_add_f32_e32 v8, 1.0, v8
	v_rcp_f32_e32 v9, v8
	s_nop 0
	s_nop 0
	v_mul_f32_e32 v3, v3, v9
	v_mul_f32_e32 v8, v3, v3
	v_pk_mul_f32 v[10:11], v[90:91], v[12:13]
	s_nop 0
	v_mov_b32_dpp v8, v8 quad_perm:[1,0,3,2] row_mask:0xf bank_mask:0xf bound_ctrl:1
	v_fmac_f32_e32 v8, v3, v3
	s_nop 1
	v_add_f32_dpp v8, v8, v8 quad_perm:[2,3,0,1] row_mask:0xf bank_mask:0xf bound_ctrl:1
	s_nop 1
	v_add_f32_dpp v8, v8, v8 row_half_mirror row_mask:0xf bank_mask:0xf bound_ctrl:1
	s_nop 1
	v_add_f32_dpp v8, v8, v8 row_mirror row_mask:0xf bank_mask:0xf bound_ctrl:1
	s_nop 0
	v_readlane_b32 s1, v8, 16
	v_readlane_b32 s6, v8, 48
	v_readlane_b32 s2, v8, 0
	v_readlane_b32 s3, v8, 32
	v_mov_b32_e32 v8, s1
	v_mov_b32_e32 v9, s6
	v_pk_add_f32 v[8:9], s[2:3], v[8:9]
	s_nop 0
	v_add_f32_e32 v8, v8, v9
	v_add_f32_e32 v8, 0x358637bd, v8
	s_nop 0
	v_rsq_f32_e32 v8, v8
	s_nop 0
	v_mul_f32_e32 v3, v3, v8
	ds_write2_b32 v18, v7, v3 offset1:65
	v_bfe_u32 v7, v3, 16, 1
	v_pk_mul_f32 v[8:9], v[90:91], v[14:15]
	v_and_b32_e32 v15, 0xffff0000, v121
	v_lshlrev_b32_e32 v14, 16, v121
	v_add3_u32 v3, v3, v7, s15
	v_add_u32_e32 v7, s61, v5
	v_pk_mov_b32 v[12:13], v[14:15], v[12:13] op_sel:[1,0]
	ds_write_b16_d16_hi v7, v3
	v_pk_mul_f32 v[16:17], v[92:93], v[12:13]
	v_add_f32_e32 v7, v8, v9
	v_add_f32_e32 v7, v17, v7
	v_add_f32_e32 v7, v16, v7
	v_mul_f32_e32 v8, 0xbfb8aa3b, v7
	v_exp_f32_e32 v8, v8
	v_add_u32_e32 v3, s91, v5
	v_add_f32_e32 v8, 1.0, v8
	v_rcp_f32_e32 v9, v8
	s_nop 0
	s_nop 0
	v_mul_f32_e32 v7, v7, v9
	v_mul_f32_e32 v8, v7, v7
	s_nop 1
	v_mov_b32_dpp v8, v8 quad_perm:[1,0,3,2] row_mask:0xf bank_mask:0xf bound_ctrl:1
	v_fmac_f32_e32 v8, v7, v7
	s_nop 1
	v_add_f32_dpp v8, v8, v8 quad_perm:[2,3,0,1] row_mask:0xf bank_mask:0xf bound_ctrl:1
	s_nop 1
	v_add_f32_dpp v8, v8, v8 row_half_mirror row_mask:0xf bank_mask:0xf bound_ctrl:1
	s_nop 1
	v_add_f32_dpp v8, v8, v8 row_mirror row_mask:0xf bank_mask:0xf bound_ctrl:1
	s_nop 0
	v_readlane_b32 s1, v8, 16
	v_readlane_b32 s6, v8, 48
	v_readlane_b32 s2, v8, 0
	v_readlane_b32 s3, v8, 32
	v_mov_b32_e32 v8, s1
	v_mov_b32_e32 v9, s6
	v_pk_add_f32 v[8:9], s[2:3], v[8:9]
	s_nop 0
	v_add_f32_e32 v8, v8, v9
	v_add_f32_e32 v8, 0x358637bd, v8
	s_nop 0
	v_rsq_f32_e32 v8, v8
	s_nop 0
	v_mul_f32_e32 v7, v7, v8
	v_bfe_u32 v8, v7, 16, 1
	v_add3_u32 v8, v7, v8, s15
	ds_write_b16_d16_hi v3, v8
	v_pk_mul_f32 v[8:9], v[92:93], v[14:15]
	v_add_f32_e32 v3, v10, v11
	v_add_f32_e32 v3, v9, v3
	v_add_f32_e32 v3, v8, v3
	v_mul_f32_e32 v8, 0xbfb8aa3b, v3
	v_exp_f32_e32 v8, v8
	s_nop 0
	v_add_f32_e32 v8, 1.0, v8
	v_rcp_f32_e32 v9, v8
	s_nop 0
	s_nop 0
	v_mul_f32_e32 v3, v3, v9
	v_mul_f32_e32 v8, v3, v3
	v_pk_mul_f32 v[10:11], v[90:91], v[14:15]
	s_nop 0
	v_mov_b32_dpp v8, v8 quad_perm:[1,0,3,2] row_mask:0xf bank_mask:0xf bound_ctrl:1
	v_fmac_f32_e32 v8, v3, v3
	s_nop 1
	v_add_f32_dpp v8, v8, v8 quad_perm:[2,3,0,1] row_mask:0xf bank_mask:0xf bound_ctrl:1
	s_nop 1
	v_add_f32_dpp v8, v8, v8 row_half_mirror row_mask:0xf bank_mask:0xf bound_ctrl:1
	s_nop 1
	v_add_f32_dpp v8, v8, v8 row_mirror row_mask:0xf bank_mask:0xf bound_ctrl:1
	s_nop 0
	v_readlane_b32 s1, v8, 16
	v_readlane_b32 s6, v8, 48
	v_readlane_b32 s2, v8, 0
	v_readlane_b32 s3, v8, 32
	v_mov_b32_e32 v8, s1
	v_mov_b32_e32 v9, s6
	v_pk_add_f32 v[8:9], s[2:3], v[8:9]
	s_nop 0
	v_add_f32_e32 v8, v8, v9
	v_add_f32_e32 v8, 0x358637bd, v8
	s_nop 0
	v_rsq_f32_e32 v8, v8
	s_nop 0
	v_mul_f32_e32 v3, v3, v8
	ds_write2_b32 v18, v7, v3 offset0:130 offset1:195
	v_bfe_u32 v7, v3, 16, 1
	v_pk_mul_f32 v[8:9], v[90:91], v[12:13]
	v_and_b32_e32 v13, 0xffff0000, v122
	v_lshlrev_b32_e32 v12, 16, v122
	v_add3_u32 v3, v3, v7, s15
	v_add_u32_e32 v7, s92, v5
	v_pk_mov_b32 v[14:15], v[12:13], v[14:15] op_sel:[1,0]
; #define LAS __attribute__((address_space(3)))
; __device__ __forceinline__ float bf2f(bf16 v) { return __uint_as_float(((unsigned)v) << 16); }
; __device__ __forceinline__ unsigned f2bf(float f) { unsigned u = __float_as_uint(f); return (u + 0x7fffu + ((u >> 16) & 1u)) >> 16; }
; __device__ __forceinline__ float siluf_(float x) { return x / (1.0f + __expf(-x)); }
; __device__ __forceinline__ int wy_producer_task(const Ctx& c, int l, int tk, WyPre& P, unsigned* head) {
;     ...
;     for (int j = 0; j < 3; ++j) { float xv[11];
; #pragma unroll
;         for (int r = 0; r < 11; ++r) xv[r] = bf2f((bf16)P.hx[j][r]);
; #pragma unroll
;         for (int r = 0; r < 8; ++r) { const int i = 8 * wid + r;
;             float y = siluf_(P.cw[j][0] * xv[r] + P.cw[j][1] * xv[r + 1] + P.cw[j][2] * xv[r + 2] + P.cw[j][3] * xv[r + 3]);
;             if (j < 2) y *= rsqrtf(wave_sum_fast(y * y) + RMS_EPS) * (j == 0 ? 0.125f : 1.0f);
;             if (j == 0) QF[i * 65 + lane] = y;
;             else if (j == 1) { KF[i * 65 + lane] = y; *(LAS bf16*)(KIMG + (lane >> 3) * 1024 + i * 16 + (lane & 7) * 2) = (bf16)f2bf(y); }
;             else VF[i * 65 + lane] = y; } }
	ds_write_b16_d16_hi v7, v3
	v_pk_mul_f32 v[16:17], v[92:93], v[14:15]
	v_add_f32_e32 v7, v8, v9
	v_add_f32_e32 v7, v17, v7
	v_add_f32_e32 v7, v16, v7
	v_mul_f32_e32 v8, 0xbfb8aa3b, v7
	v_exp_f32_e32 v8, v8
	v_add_u32_e32 v3, s62, v5
	v_add_f32_e32 v8, 1.0, v8
	v_rcp_f32_e32 v9, v8
	s_nop 0
	s_nop 0
	v_mul_f32_e32 v7, v7, v9
	v_mul_f32_e32 v8, v7, v7
	s_nop 1
	v_mov_b32_dpp v8, v8 quad_perm:[1,0,3,2] row_mask:0xf bank_mask:0xf bound_ctrl:1
	v_fmac_f32_e32 v8, v7, v7
	s_nop 1
	v_add_f32_dpp v8, v8, v8 quad_perm:[2,3,0,1] row_mask:0xf bank_mask:0xf bound_ctrl:1
	s_nop 1
	v_add_f32_dpp v8, v8, v8 row_half_mirror row_mask:0xf bank_mask:0xf bound_ctrl:1
	s_nop 1
	v_add_f32_dpp v8, v8, v8 row_mirror row_mask:0xf bank_mask:0xf bound_ctrl:1
	s_nop 0
	v_readlane_b32 s1, v8, 16
	v_readlane_b32 s6, v8, 48
	v_readlane_b32 s2, v8, 0
	v_readlane_b32 s3, v8, 32
	v_mov_b32_e32 v8, s1
	v_mov_b32_e32 v9, s6
	v_pk_add_f32 v[8:9], s[2:3], v[8:9]
	s_nop 0
	v_add_f32_e32 v8, v8, v9
	v_add_f32_e32 v8, 0x358637bd, v8
	s_nop 0
	v_rsq_f32_e32 v8, v8
	s_nop 0
	v_mul_f32_e32 v7, v7, v8
	v_bfe_u32 v8, v7, 16, 1
	v_add3_u32 v8, v7, v8, s15
	ds_write_b16_d16_hi v3, v8
	v_pk_mul_f32 v[8:9], v[92:93], v[12:13]
	v_add_f32_e32 v3, v10, v11
	v_add_f32_e32 v3, v9, v3
	v_add_f32_e32 v3, v8, v3
	v_mul_f32_e32 v8, 0xbfb8aa3b, v3
	v_exp_f32_e32 v8, v8
	s_nop 0
	v_add_f32_e32 v8, 1.0, v8
	v_rcp_f32_e32 v9, v8
	s_nop 0
	s_nop 0
	v_mul_f32_e32 v3, v3, v9
	v_mul_f32_e32 v8, v3, v3
	v_lshlrev_b32_e32 v13, 16, v104
	s_nop 0
	v_mov_b32_dpp v8, v8 quad_perm:[1,0,3,2] row_mask:0xf bank_mask:0xf bound_ctrl:1
	v_fmac_f32_e32 v8, v3, v3
	s_nop 1
	v_add_f32_dpp v8, v8, v8 quad_perm:[2,3,0,1] row_mask:0xf bank_mask:0xf bound_ctrl:1
	s_nop 1
	v_add_f32_dpp v8, v8, v8 row_half_mirror row_mask:0xf bank_mask:0xf bound_ctrl:1
	s_nop 1
	v_add_f32_dpp v8, v8, v8 row_mirror row_mask:0xf bank_mask:0xf bound_ctrl:1
	s_nop 0
	v_readlane_b32 s1, v8, 16
	v_readlane_b32 s6, v8, 48
	v_readlane_b32 s2, v8, 0
	v_readlane_b32 s3, v8, 32
	v_mov_b32_e32 v8, s1
	v_mov_b32_e32 v9, s6
	v_pk_add_f32 v[8:9], s[2:3], v[8:9]
	s_nop 0
	v_add_f32_e32 v8, v8, v9
	v_add_f32_e32 v8, 0x358637bd, v8
	s_nop 0
	v_rsq_f32_e32 v8, v8
	s_nop 0
	v_mul_f32_e32 v3, v3, v8
	v_add_u32_e32 v8, 0x800, v6
	ds_write2_b32 v8, v7, v3 offset0:4 offset1:69
	v_bfe_u32 v7, v3, 16, 1
	v_add3_u32 v3, v3, v7, s15
	v_add_u32_e32 v7, s63, v5
	ds_write_b16_d16_hi v7, v3
	v_pk_mul_f32 v[8:9], v[90:91], v[14:15]
	v_mov_b32_e32 v3, v12
	v_pk_mul_f32 v[2:3], v[92:93], v[2:3]
	v_add_f32_e32 v7, v8, v9
	v_add_f32_e32 v3, v3, v7
	v_add_f32_e32 v2, v2, v3
	v_mul_f32_e32 v3, 0xbfb8aa3b, v2
	v_exp_f32_e32 v3, v3
	v_lshlrev_b32_e32 v12, 16, v102
	v_add_f32_e32 v3, 1.0, v3
	v_rcp_f32_e32 v7, v3
	s_nop 0
	s_nop 0
	v_mul_f32_e32 v7, v2, v7
	v_mul_f32_e32 v2, v7, v7
	v_lshlrev_b32_e32 v8, 16, v97
	v_lshlrev_b32_e32 v9, 16, v100
	v_mov_b32_dpp v2, v2 quad_perm:[1,0,3,2] row_mask:0xf bank_mask:0xf bound_ctrl:1
	v_fmac_f32_e32 v2, v7, v7
	v_lshlrev_b32_e32 v10, 16, v99
	v_lshlrev_b32_e32 v11, 16, v101
	v_add_f32_dpp v2, v2, v2 quad_perm:[2,3,0,1] row_mask:0xf bank_mask:0xf bound_ctrl:1
	s_nop 1
	v_add_f32_dpp v2, v2, v2 row_half_mirror row_mask:0xf bank_mask:0xf bound_ctrl:1
	s_nop 1
	v_add_f32_dpp v2, v2, v2 row_mirror row_mask:0xf bank_mask:0xf bound_ctrl:1
	s_nop 0
	v_readlane_b32 s1, v2, 16
	v_readlane_b32 s6, v2, 48
	v_readlane_b32 s2, v2, 0
	v_readlane_b32 s3, v2, 32
	v_mov_b32_e32 v2, s1
	v_mov_b32_e32 v3, s6
	v_pk_add_f32 v[2:3], s[2:3], v[2:3]
	s_nop 0
	v_add_f32_e32 v2, v2, v3
	v_add_f32_e32 v2, 0x358637bd, v2
	s_nop 0
	v_rsq_f32_e32 v2, v2
	s_nop 0
	v_mul_f32_e32 v2, v7, v2
	v_lshlrev_b32_e32 v7, 16, v98
	s_waitcnt vmcnt(3)
	v_mul_f32_e32 v7, v108, v7
	s_waitcnt vmcnt(2)
	v_fmac_f32_e32 v7, v110, v8
	s_waitcnt vmcnt(1)
	v_fmac_f32_e32 v7, v112, v9
	s_waitcnt vmcnt(0)
	v_fmac_f32_e32 v7, v113, v10
	v_mul_f32_e32 v14, 0xbfb8aa3b, v7
	v_exp_f32_e32 v14, v14
	ds_write_b32 v6, v2 offset:2584
	v_lshlrev_b32_e32 v6, 16, v103
	v_bfe_u32 v3, v2, 16, 1
	v_add_f32_e32 v14, 1.0, v14
	v_rcp_f32_e32 v15, v14
	v_add3_u32 v2, v2, v3, s15
	v_add_u32_e32 v3, s89, v5
	v_lshlrev_b32_e32 v5, 16, v105
	s_nop 0
	v_mul_f32_e32 v7, v7, v15
	v_add_u32_e32 v14, s96, v4
	ds_write_b32 v14, v7
	v_mul_f32_e32 v7, v108, v8
	v_fmac_f32_e32 v7, v110, v9
	v_fmac_f32_e32 v7, v112, v10
	v_fmac_f32_e32 v7, v113, v11
	v_mul_f32_e32 v8, 0xbfb8aa3b, v7
	v_exp_f32_e32 v8, v8
	v_add_u32_e32 v4, s97, v4
	ds_write_b16_d16_hi v3, v2
	v_lshlrev_b32_e32 v3, 16, v106
	v_add_f32_e32 v8, 1.0, v8
	v_rcp_f32_e32 v14, v8
	v_lshlrev_b32_e32 v2, 16, v107
	s_nop 0
	v_mul_f32_e32 v7, v7, v14
	v_mul_f32_e32 v8, v108, v9
	v_fmac_f32_e32 v8, v110, v10
	v_fmac_f32_e32 v8, v112, v11
	v_fmac_f32_e32 v8, v113, v12
	v_mul_f32_e32 v9, 0xbfb8aa3b, v8
	v_exp_f32_e32 v9, v9
	s_nop 0
	v_add_f32_e32 v9, 1.0, v9
	v_rcp_f32_e32 v14, v9
	s_nop 0
	s_nop 0
	v_mul_f32_e32 v8, v8, v14
	ds_write2_b32 v4, v7, v8 offset1:65
	v_mul_f32_e32 v7, v108, v10
	v_fmac_f32_e32 v7, v110, v11
	v_fmac_f32_e32 v7, v112, v12
	v_fmac_f32_e32 v7, v113, v13
	v_mul_f32_e32 v8, 0xbfb8aa3b, v7
	v_exp_f32_e32 v8, v8
	s_nop 0
	v_add_f32_e32 v8, 1.0, v8
	v_rcp_f32_e32 v9, v8
	s_nop 0
	s_nop 0
	v_mul_f32_e32 v7, v7, v9
	v_mul_f32_e32 v8, v108, v11
	v_fmac_f32_e32 v8, v110, v12
	v_fmac_f32_e32 v8, v112, v13
	v_fmac_f32_e32 v8, v113, v6
	v_mul_f32_e32 v9, 0xbfb8aa3b, v8
	v_exp_f32_e32 v9, v9
	s_nop 0
	v_add_f32_e32 v9, 1.0, v9
	v_rcp_f32_e32 v10, v9
	s_nop 0
	s_nop 0
	v_mul_f32_e32 v8, v8, v10
	ds_write2_b32 v4, v7, v8 offset0:130 offset1:195
	v_mul_f32_e32 v7, v108, v12
	v_fmac_f32_e32 v7, v110, v13
	v_fmac_f32_e32 v7, v112, v6
	v_fmac_f32_e32 v7, v113, v5
	v_mul_f32_e32 v8, 0xbfb8aa3b, v7
	v_exp_f32_e32 v8, v8
	s_nop 0
	v_add_f32_e32 v8, 1.0, v8
	v_rcp_f32_e32 v9, v8
	s_nop 0
	s_nop 0
	v_mul_f32_e32 v7, v7, v9
	v_mul_f32_e32 v8, v108, v13
	v_fmac_f32_e32 v8, v110, v6
	v_fmac_f32_e32 v8, v112, v5
	v_fmac_f32_e32 v8, v113, v3
	v_mul_f32_e32 v9, 0xbfb8aa3b, v8
	v_exp_f32_e32 v9, v9
	v_mul_f32_e32 v6, v108, v6
	v_fmac_f32_e32 v6, v110, v5
	v_fmac_f32_e32 v6, v112, v3
	v_add_f32_e32 v9, 1.0, v9
	v_rcp_f32_e32 v10, v9
	v_fmac_f32_e32 v6, v113, v2
	v_mul_f32_e32 v2, 0xbfb8aa3b, v6
	v_exp_f32_e32 v2, v2
	s_nop 0
	v_add_f32_e32 v2, 1.0, v2
	v_div_scale_f32 v3, s[2:3], v2, v2, v6
	v_rcp_f32_e32 v5, v3
	s_nop 0
	v_mul_f32_e32 v8, v8, v10
	v_add_u32_e32 v9, 0x400, v4
	ds_write2_b32 v9, v7, v8 offset0:4 offset1:69
	v_fma_f32 v7, -v3, v5, 1.0
	v_fmac_f32_e32 v5, v7, v5
	v_div_scale_f32 v7, vcc, v6, v2, v6
	v_mul_f32_e32 v8, v7, v5
	v_fma_f32 v9, -v3, v8, v7
	v_fmac_f32_e32 v8, v9, v5
	v_fma_f32 v3, -v3, v8, v7
	v_div_fmas_f32 v3, v3, v5, v8
	v_div_fixup_f32 v2, v3, v2, v6
	s_and_b64 vcc, exec, s[38:39]
	ds_write_b32 v4, v2 offset:1560
	s_cbranch_vccz .LBB0_1093
	s_and_saveexec_b64 s[2:3], s[4:5]

; __device__ __forceinline__ float bf2f(bf16 v) { return __uint_as_float(((unsigned)v) << 16); }
; __device__ __forceinline__ unsigned f2bf(float f) { unsigned u = __float_as_uint(f); return (u + 0x7fffu + ((u >> 16) & 1u)) >> 16; }
; __device__ __forceinline__ float siluf_(float x) { return x / (1.0f + __expf(-x)); }
; __device__ __forceinline__ void p4b_gdn_norm(const Ctx& c0, int l) {
;     ...
;     for (int it0 = gw; it0 < MPR * 8; it0 += 8 * NGW) {
;         float ov[8], zv[8];
; #pragma unroll
;         for (int u = 0; u < 8; ++u) { const int it = it0 + u * NGW; ov[u] = 0.f; zv[u] = 0.f;
;             if (it < MPR * 8) { const int hh = it & 7, m = it >> 3; ov[u] = __builtin_nontemporal_load(OG + (size_t)m * 512 + hh * 64 + lane); zv[u] = bf2f(__builtin_nontemporal_load(H + (size_t)m * HW + HGZ + hh * 64 + lane)); } }
; #pragma unroll
;         for (int u = 0; u < 8; ++u) { const int it = it0 + u * NGW;
;             if (it < MPR * 8) { const int hh = it & 7, m = it >> 3; const float ms = wave_sum_fast(ov[u] * ov[u]) * (1.f / 64.f);
;                 MIX[(size_t)m * DM + 512 + hh * 64 + lane] = (bf16)f2bf(ov[u] * rsqrtf(ms + RMS_EPS) * nw * siluf_(zv[u])); } } }
.LBB0_1550:
	s_waitcnt vmcnt(0)
	v_lshlrev_b32_e32 v0, 16, v0
	v_lshlrev_b32_e32 v15, 16, v15
	v_lshlrev_b32_e32 v2, 16, v2
	v_lshlrev_b32_e32 v3, 16, v3
	v_lshlrev_b32_e32 v4, 16, v4
	v_lshlrev_b32_e32 v5, 16, v5
	v_lshlrev_b32_e32 v6, 16, v6
	v_lshlrev_b32_e32 v7, 16, v7
	v_mul_f32_e32 v16, v14, v14
	v_lshl_add_u64 v[24:25], v[22:23], 0, s[30:31]
	s_nop 0
	v_mov_b32_dpp v16, v16 quad_perm:[1,0,3,2] row_mask:0xf bank_mask:0xf bound_ctrl:1
	v_fmac_f32_e32 v16, v14, v14
	s_nop 1
	v_add_f32_dpp v16, v16, v16 quad_perm:[2,3,0,1] row_mask:0xf bank_mask:0xf bound_ctrl:1
	s_nop 1
	v_add_f32_dpp v16, v16, v16 row_half_mirror row_mask:0xf bank_mask:0xf bound_ctrl:1
	s_nop 1
	v_add_f32_dpp v16, v16, v16 row_mirror row_mask:0xf bank_mask:0xf bound_ctrl:1
	s_nop 0
	v_readlane_b32 s30, v16, 16
	v_readlane_b32 s33, v16, 48
	v_readlane_b32 s28, v16, 0
	v_readlane_b32 s29, v16, 32
	v_mov_b32_e32 v26, s30
	v_mov_b32_e32 v27, s33
	v_pk_add_f32 v[26:27], s[28:29], v[26:27]
	s_mov_b32 s28, 0x800000
	v_add_f32_e32 v16, v26, v27
	v_fmamk_f32 v16, v16, 0x3c800000, v221
	s_nop 0
	v_rsq_f32_e32 v16, v16
	s_nop 0
	v_mul_f32_e32 v14, v14, v16
	v_mul_f32_e32 v16, 0xbfb8aa3b, v0
	v_exp_f32_e32 v16, v16
	v_mul_f32_e32 v14, v36, v14
	v_add_f32_e32 v16, 1.0, v16
	v_rcp_f32_e32 v26, v16
	s_nop 0
	s_nop 0
	v_mul_f32_e32 v0, v0, v26
	v_mul_f32_e32 v0, v0, v14
	v_bfe_u32 v14, v0, 16, 1
	v_add3_u32 v0, v0, v14, s15
	v_lshl_add_u64 v[26:27], v[24:25], 0, s[36:37]
	s_andn2_b64 vcc, exec, s[38:39]
	global_store_short_d16_hi v[26:27], v0, off
	s_cbranch_vccz .LBB0_1557
	s_andn2_b64 vcc, exec, s[24:25]
	s_movk_i32 s33, 0x4000
	s_cbranch_vccz .LBB0_1558

; __device__ __forceinline__ float bf2f(bf16 v) { return __uint_as_float(((unsigned)v) << 16); }
; __device__ __forceinline__ unsigned f2bf(float f) { unsigned u = __float_as_uint(f); return (u + 0x7fffu + ((u >> 16) & 1u)) >> 16; }
; __device__ __forceinline__ float siluf_(float x) { return x / (1.0f + __expf(-x)); }
; __device__ __forceinline__ void p4b_gdn_norm(const Ctx& c0, int l) {
;     ...
;     for (int it0 = gw; it0 < MPR * 8; it0 += 8 * NGW) {
;         float ov[8], zv[8];
; #pragma unroll
;         for (int u = 0; u < 8; ++u) { const int it = it0 + u * NGW; ov[u] = 0.f; zv[u] = 0.f;
;             if (it < MPR * 8) { const int hh = it & 7, m = it >> 3; ov[u] = __builtin_nontemporal_load(OG + (size_t)m * 512 + hh * 64 + lane); zv[u] = bf2f(__builtin_nontemporal_load(H + (size_t)m * HW + HGZ + hh * 64 + lane)); } }
; #pragma unroll
;         for (int u = 0; u < 8; ++u) { const int it = it0 + u * NGW;
;             if (it < MPR * 8) { const int hh = it & 7, m = it >> 3; const float ms = wave_sum_fast(ov[u] * ov[u]) * (1.f / 64.f);
;                 MIX[(size_t)m * DM + 512 + hh * 64 + lane] = (bf16)f2bf(ov[u] * rsqrtf(ms + RMS_EPS) * nw * siluf_(zv[u])); } } }
.LBB0_1557:
	v_mul_f32_e32 v0, v17, v17
	s_ashr_i32 s28, s27, 3
	s_nop 0
	v_mov_b32_dpp v0, v0 quad_perm:[1,0,3,2] row_mask:0xf bank_mask:0xf bound_ctrl:1
	v_fmac_f32_e32 v0, v17, v17
	s_nop 1
	v_add_f32_dpp v0, v0, v0 quad_perm:[2,3,0,1] row_mask:0xf bank_mask:0xf bound_ctrl:1
	s_nop 1
	v_add_f32_dpp v0, v0, v0 row_half_mirror row_mask:0xf bank_mask:0xf bound_ctrl:1
	s_nop 1
	v_add_f32_dpp v0, v0, v0 row_mirror row_mask:0xf bank_mask:0xf bound_ctrl:1
	s_nop 0
	v_readlane_b32 s27, v0, 16
	v_readlane_b32 s29, v0, 48
	v_readlane_b32 s36, v0, 0
	v_readlane_b32 s37, v0, 32
	v_mov_b32_e32 v26, s27
	v_mov_b32_e32 v27, s29
	v_pk_add_f32 v[26:27], s[36:37], v[26:27]
	s_mov_b32 s27, 0x800000
	v_add_f32_e32 v0, v26, v27
	v_fmamk_f32 v0, v0, 0x3c800000, v221
	s_ashr_i32 s29, s28, 31
	v_rsq_f32_e32 v0, v0
	s_lshl_b64 s[28:29], s[28:29], 11
	v_mul_f32_e32 v14, 0xbfb8aa3b, v15
	v_exp_f32_e32 v14, v14
	v_mul_f32_e32 v0, v17, v0
	v_mul_f32_e32 v0, v36, v0
	v_add_f32_e32 v14, 1.0, v14
	v_rcp_f32_e32 v16, v14
	s_nop 0
	s_nop 0
	v_mul_f32_e32 v14, v15, v16
	v_mul_f32_e32 v0, v14, v0
	v_bfe_u32 v14, v0, 16, 1
	v_add3_u32 v0, v0, v14, s15
	v_lshl_add_u64 v[14:15], v[24:25], 0, s[28:29]
	global_store_short_d16_hi v[14:15], v0, off
	s_andn2_b64 vcc, exec, s[24:25]
	s_movk_i32 s33, 0x4000
	s_cbranch_vccnz .LBB0_1552
.LBB0_1558:
	v_mul_f32_e32 v0, v12, v12
	s_ashr_i32 s24, s26, 3
	s_nop 0
	v_mov_b32_dpp v0, v0 quad_perm:[1,0,3,2] row_mask:0xf bank_mask:0xf bound_ctrl:1
	v_fmac_f32_e32 v0, v12, v12
	s_nop 1
	v_add_f32_dpp v0, v0, v0 quad_perm:[2,3,0,1] row_mask:0xf bank_mask:0xf bound_ctrl:1
	s_nop 1
	v_add_f32_dpp v0, v0, v0 row_half_mirror row_mask:0xf bank_mask:0xf bound_ctrl:1
	s_nop 1
	v_add_f32_dpp v0, v0, v0 row_mirror row_mask:0xf bank_mask:0xf bound_ctrl:1
	s_nop 0
	v_readlane_b32 s25, v0, 16
	v_readlane_b32 s28, v0, 48
	v_readlane_b32 s26, v0, 0
	v_readlane_b32 s27, v0, 32
	v_mov_b32_e32 v14, s25
	v_mov_b32_e32 v15, s28
	v_pk_add_f32 v[14:15], s[26:27], v[14:15]
	s_mov_b32 s25, 0x800000
	v_add_f32_e32 v0, v14, v15
	v_fmamk_f32 v0, v0, 0x3c800000, v221
	s_ashr_i32 s25, s24, 31
	v_rsq_f32_e32 v0, v0
	s_lshl_b64 s[24:25], s[24:25], 11
	v_mul_f32_e32 v0, v12, v0
	v_mul_f32_e32 v12, 0xbfb8aa3b, v2
	v_exp_f32_e32 v12, v12
	v_mul_f32_e32 v0, v36, v0
	v_add_f32_e32 v12, 1.0, v12
	v_rcp_f32_e32 v14, v12
	s_nop 0
	s_nop 0
	v_mul_f32_e32 v2, v2, v14
	v_mul_f32_e32 v0, v2, v0
	v_bfe_u32 v2, v0, 16, 1
	v_add3_u32 v0, v0, v2, s15
	v_lshl_add_u64 v[14:15], v[24:25], 0, s[24:25]
	global_store_short_d16_hi v[14:15], v0, off
	s_andn2_b64 vcc, exec, s[16:17]
	s_cbranch_vccnz .LBB0_1553
.LBB0_1559:
	v_mul_f32_e32 v0, v13, v13
	s_ashr_i32 s16, s23, 3
	s_nop 0
	v_mov_b32_dpp v0, v0 quad_perm:[1,0,3,2] row_mask:0xf bank_mask:0xf bound_ctrl:1
	v_fmac_f32_e32 v0, v13, v13
	s_nop 1
	v_add_f32_dpp v0, v0, v0 quad_perm:[2,3,0,1] row_mask:0xf bank_mask:0xf bound_ctrl:1
	s_nop 1
	v_add_f32_dpp v0, v0, v0 row_half_mirror row_mask:0xf bank_mask:0xf bound_ctrl:1
	s_nop 1
	v_add_f32_dpp v0, v0, v0 row_mirror row_mask:0xf bank_mask:0xf bound_ctrl:1
	s_nop 0
	v_readlane_b32 s17, v0, 16
	v_readlane_b32 s23, v0, 48
	v_readlane_b32 s24, v0, 0
	v_readlane_b32 s25, v0, 32
	v_mov_b32_e32 v14, s17
	v_mov_b32_e32 v15, s23
	v_pk_add_f32 v[14:15], s[24:25], v[14:15]
	s_mov_b32 s17, 0x800000
	v_add_f32_e32 v0, v14, v15
	v_fmamk_f32 v0, v0, 0x3c800000, v221
	s_ashr_i32 s17, s16, 31
	v_rsq_f32_e32 v0, v0
	s_lshl_b64 s[16:17], s[16:17], 11
	v_mul_f32_e32 v2, 0xbfb8aa3b, v3
	v_exp_f32_e32 v2, v2
	v_mul_f32_e32 v0, v13, v0
	v_mul_f32_e32 v0, v36, v0
	v_add_f32_e32 v2, 1.0, v2
	v_rcp_f32_e32 v12, v2
	s_nop 0
	s_nop 0
	v_mul_f32_e32 v2, v3, v12
	v_mul_f32_e32 v0, v2, v0
	v_bfe_u32 v2, v0, 16, 1
	v_add3_u32 v0, v0, v2, s15
	v_lshl_add_u64 v[2:3], v[24:25], 0, s[16:17]
	global_store_short_d16_hi v[2:3], v0, off
	s_andn2_b64 vcc, exec, s[10:11]
	s_cbranch_vccnz .LBB0_1554
; __device__ __forceinline__ float bf2f(bf16 v) { return __uint_as_float(((unsigned)v) << 16); }
; __device__ __forceinline__ unsigned f2bf(float f) { unsigned u = __float_as_uint(f); return (u + 0x7fffu + ((u >> 16) & 1u)) >> 16; }
; __device__ __forceinline__ float siluf_(float x) { return x / (1.0f + __expf(-x)); }
; __device__ __forceinline__ void p4b_gdn_norm(const Ctx& c0, int l) {
;     ...
;     for (int it0 = gw; it0 < MPR * 8; it0 += 8 * NGW) {
;         float ov[8], zv[8];
; #pragma unroll
;         for (int u = 0; u < 8; ++u) { const int it = it0 + u * NGW; ov[u] = 0.f; zv[u] = 0.f;
;             if (it < MPR * 8) { const int hh = it & 7, m = it >> 3; ov[u] = __builtin_nontemporal_load(OG + (size_t)m * 512 + hh * 64 + lane); zv[u] = bf2f(__builtin_nontemporal_load(H + (size_t)m * HW + HGZ + hh * 64 + lane)); } }
; #pragma unroll
;         for (int u = 0; u < 8; ++u) { const int it = it0 + u * NGW;
;             if (it < MPR * 8) { const int hh = it & 7, m = it >> 3; const float ms = wave_sum_fast(ov[u] * ov[u]) * (1.f / 64.f);
;                 MIX[(size_t)m * DM + 512 + hh * 64 + lane] = (bf16)f2bf(ov[u] * rsqrtf(ms + RMS_EPS) * nw * siluf_(zv[u])); } } }
.LBB0_1560:
	v_mul_f32_e32 v0, v10, v10
	s_ashr_i32 s10, s22, 3
	s_nop 0
	v_mov_b32_dpp v0, v0 quad_perm:[1,0,3,2] row_mask:0xf bank_mask:0xf bound_ctrl:1
	v_fmac_f32_e32 v0, v10, v10
	s_nop 1
	v_add_f32_dpp v0, v0, v0 quad_perm:[2,3,0,1] row_mask:0xf bank_mask:0xf bound_ctrl:1
	s_nop 1
	v_add_f32_dpp v0, v0, v0 row_half_mirror row_mask:0xf bank_mask:0xf bound_ctrl:1
	s_nop 1
	v_add_f32_dpp v0, v0, v0 row_mirror row_mask:0xf bank_mask:0xf bound_ctrl:1
	s_nop 0
	v_readlane_b32 s11, v0, 16
	v_readlane_b32 s22, v0, 48
	v_readlane_b32 s16, v0, 0
	v_readlane_b32 s17, v0, 32
	v_mov_b32_e32 v2, s11
	v_mov_b32_e32 v3, s22
	v_pk_add_f32 v[2:3], s[16:17], v[2:3]
	s_mov_b32 s11, 0x800000
	v_add_f32_e32 v0, v2, v3
	v_fmamk_f32 v0, v0, 0x3c800000, v221
	s_ashr_i32 s11, s10, 31
	v_rsq_f32_e32 v0, v0
	s_lshl_b64 s[10:11], s[10:11], 11
	v_mul_f32_e32 v2, 0xbfb8aa3b, v4
	v_exp_f32_e32 v2, v2
	v_mul_f32_e32 v0, v10, v0
	v_mul_f32_e32 v0, v36, v0
	v_add_f32_e32 v2, 1.0, v2
	v_rcp_f32_e32 v3, v2
	s_nop 0
	s_nop 0
	v_mul_f32_e32 v2, v4, v3
	v_mul_f32_e32 v0, v2, v0
	v_bfe_u32 v2, v0, 16, 1
	v_add3_u32 v0, v0, v2, s15
	v_lshl_add_u64 v[2:3], v[24:25], 0, s[10:11]
	global_store_short_d16_hi v[2:3], v0, off
	s_andn2_b64 vcc, exec, s[6:7]
	s_cbranch_vccnz .LBB0_1555
.LBB0_1561:
	v_mul_f32_e32 v0, v11, v11
	s_ashr_i32 s6, s20, 3
	s_nop 0
	v_mov_b32_dpp v0, v0 quad_perm:[1,0,3,2] row_mask:0xf bank_mask:0xf bound_ctrl:1
	v_fmac_f32_e32 v0, v11, v11
	s_nop 1
	v_add_f32_dpp v0, v0, v0 quad_perm:[2,3,0,1] row_mask:0xf bank_mask:0xf bound_ctrl:1
	s_nop 1
	v_add_f32_dpp v0, v0, v0 row_half_mirror row_mask:0xf bank_mask:0xf bound_ctrl:1
	s_nop 1
	v_add_f32_dpp v0, v0, v0 row_mirror row_mask:0xf bank_mask:0xf bound_ctrl:1
	s_nop 0
	v_readlane_b32 s7, v0, 16
	v_readlane_b32 s16, v0, 48
	v_readlane_b32 s10, v0, 0
	v_readlane_b32 s11, v0, 32
	v_mov_b32_e32 v2, s7
	v_mov_b32_e32 v3, s16
	v_pk_add_f32 v[2:3], s[10:11], v[2:3]
	s_mov_b32 s7, 0x800000
	v_add_f32_e32 v0, v2, v3
	v_fmamk_f32 v0, v0, 0x3c800000, v221
	s_ashr_i32 s7, s6, 31
	v_rsq_f32_e32 v0, v0
	s_lshl_b64 s[6:7], s[6:7], 11
	v_mul_f32_e32 v2, 0xbfb8aa3b, v5
	v_exp_f32_e32 v2, v2
	v_mul_f32_e32 v0, v11, v0
	v_mul_f32_e32 v0, v36, v0
	v_add_f32_e32 v2, 1.0, v2
	v_rcp_f32_e32 v3, v2
	s_nop 0
	s_nop 0
	v_mul_f32_e32 v2, v5, v3
	v_mul_f32_e32 v0, v2, v0
	v_bfe_u32 v2, v0, 16, 1
	v_add3_u32 v0, v0, v2, s15
	v_lshl_add_u64 v[2:3], v[24:25], 0, s[6:7]
	global_store_short_d16_hi v[2:3], v0, off
	s_andn2_b64 vcc, exec, s[4:5]
	s_cbranch_vccnz .LBB0_1556
.LBB0_1562:
	v_mul_f32_e32 v0, v8, v8
	s_ashr_i32 s4, s19, 3
	s_nop 0
	v_mov_b32_dpp v0, v0 quad_perm:[1,0,3,2] row_mask:0xf bank_mask:0xf bound_ctrl:1
	v_fmac_f32_e32 v0, v8, v8
	s_nop 1
	v_add_f32_dpp v0, v0, v0 quad_perm:[2,3,0,1] row_mask:0xf bank_mask:0xf bound_ctrl:1
	s_nop 1
	v_add_f32_dpp v0, v0, v0 row_half_mirror row_mask:0xf bank_mask:0xf bound_ctrl:1
	s_nop 1
	v_add_f32_dpp v0, v0, v0 row_mirror row_mask:0xf bank_mask:0xf bound_ctrl:1
	s_nop 0
	v_readlane_b32 s5, v0, 16
	v_readlane_b32 s10, v0, 48
	v_readlane_b32 s6, v0, 0
	v_readlane_b32 s7, v0, 32
	v_mov_b32_e32 v2, s5
	v_mov_b32_e32 v3, s10
	v_pk_add_f32 v[2:3], s[6:7], v[2:3]
	s_mov_b32 s5, 0x800000
	v_add_f32_e32 v0, v2, v3
	v_fmamk_f32 v0, v0, 0x3c800000, v221
	s_ashr_i32 s5, s4, 31
	v_rsq_f32_e32 v0, v0
	s_lshl_b64 s[4:5], s[4:5], 11
	v_mul_f32_e32 v2, 0xbfb8aa3b, v6
	v_exp_f32_e32 v2, v2
	v_mul_f32_e32 v0, v8, v0
	v_mul_f32_e32 v0, v36, v0
	v_add_f32_e32 v2, 1.0, v2
	v_rcp_f32_e32 v3, v2
	s_nop 0
	s_nop 0
	v_mul_f32_e32 v2, v6, v3
	v_mul_f32_e32 v0, v2, v0
	v_bfe_u32 v2, v0, 16, 1
	v_add3_u32 v0, v0, v2, s15
	v_lshl_add_u64 v[2:3], v[24:25], 0, s[4:5]
	global_store_short_d16_hi v[2:3], v0, off
	s_andn2_b64 vcc, exec, s[2:3]
	s_cbranch_vccnz .LBB0_1528
.LBB0_1563:
	v_mul_f32_e32 v0, v9, v9
	s_ashr_i32 s2, s9, 3
	s_nop 0
	v_mov_b32_dpp v0, v0 quad_perm:[1,0,3,2] row_mask:0xf bank_mask:0xf bound_ctrl:1
	v_fmac_f32_e32 v0, v9, v9
	s_nop 1
	v_add_f32_dpp v0, v0, v0 quad_perm:[2,3,0,1] row_mask:0xf bank_mask:0xf bound_ctrl:1
	s_nop 1
	v_add_f32_dpp v0, v0, v0 row_half_mirror row_mask:0xf bank_mask:0xf bound_ctrl:1
	s_nop 1
	v_add_f32_dpp v0, v0, v0 row_mirror row_mask:0xf bank_mask:0xf bound_ctrl:1
	s_nop 0
	v_readlane_b32 s3, v0, 16
	v_readlane_b32 s6, v0, 48
	v_readlane_b32 s4, v0, 0
	v_readlane_b32 s5, v0, 32
	v_mov_b32_e32 v2, s3
	v_mov_b32_e32 v3, s6
	v_pk_add_f32 v[2:3], s[4:5], v[2:3]
	s_mov_b32 s3, 0x800000
	v_add_f32_e32 v0, v2, v3
	v_fmamk_f32 v0, v0, 0x3c800000, v221
	s_ashr_i32 s3, s2, 31
	v_rsq_f32_e32 v0, v0
	s_lshl_b64 s[2:3], s[2:3], 11
	v_mul_f32_e32 v2, 0xbfb8aa3b, v7
	v_exp_f32_e32 v2, v2
	v_mul_f32_e32 v0, v9, v0
	v_mul_f32_e32 v0, v36, v0
	v_add_f32_e32 v2, 1.0, v2
	v_rcp_f32_e32 v3, v2
	s_nop 0
	s_nop 0
	v_mul_f32_e32 v2, v7, v3
	v_mul_f32_e32 v0, v2, v0
	v_bfe_u32 v2, v0, 16, 1
	v_add3_u32 v0, v0, v2, s15
	v_lshl_add_u64 v[2:3], v[24:25], 0, s[2:3]
	global_store_short_d16_hi v[2:3], v0, off
	s_branch .LBB0_1528

;     __device__ __forceinline__ void fused(f32x4 (&acc)[2][2][4][2], const Unit& u, int wr, int wc, int fr, int fq, PG8_LAS unsigned char* lds, int wid, int lane) const {
;     ...
;                     for (int n = 0; n < 2; ++n) { const size_t o = off + bj * HALF + n * 16; const u32x2v xw = *(const u32x2v*)(XR + o); f32x4 a = acc[ai][bj][m][n];
;                         const f32x4 xv = (f32x4){__uint_as_float(xw.x << 16), __uint_as_float(xw.x & 0xffff0000u), __uint_as_float(xw.y << 16), __uint_as_float(xw.y & 0xffff0000u)};
;                         if (MODE == 1) { const u32x2v pw = *(const u32x2v*)(PP + o); const f32x4 pv = (f32x4){__uint_as_float(pw.x << 16), __uint_as_float(pw.x & 0xffff0000u), __uint_as_float(pw.y << 16), __uint_as_float(pw.y & 0xffff0000u)};
; #pragma unroll
;                             for (int j = 0; j < 4; ++j) a[j] = pv[j] / (1.0f + __expf(-a[j])); }
;                         acc[ai][bj][m][n] = xv * DN_ALPHA + a; }
.LBB0_2313:
	s_lshl_b32 s0, s4, 8
	v_readlane_b32 s1, v255, 12
	s_or_b32 s0, s0, s1
	v_lshrrev_b32_e32 v130, 2, v140
	s_lshl_b32 s38, s71, 8
	v_and_or_b32 v162, v130, 12, s0
	s_add_i32 s0, s38, s65
	v_or_b32_e32 v130, s0, v141
	v_ashrrev_i32_e32 v131, 31, v130
	v_ashrrev_i32_e32 v163, 31, v162
	v_lshlrev_b64 v[132:133], 10, v[130:131]
	v_lshl_add_u64 v[132:133], v[132:133], 0, v[162:163]
	v_lshlrev_b64 v[132:133], 1, v[132:133]
	v_lshl_add_u64 v[134:135], s[50:51], 0, v[132:133]
	v_lshl_add_u64 v[132:133], s[52:53], 0, v[132:133]
	s_barrier
	global_load_dwordx2 v[142:143], v[132:133], off
	v_mul_f32_e32 v6, 0xbfb8aa3b, v6
	v_mul_f32_e32 v7, 0xbfb8aa3b, v7
	v_exp_f32_e32 v6, v6
	v_exp_f32_e32 v7, v7
	v_mul_f32_e32 v8, 0xbfb8aa3b, v8
	v_mul_f32_e32 v9, 0xbfb8aa3b, v9
	v_exp_f32_e32 v8, v8
	v_pk_add_f32 v[6:7], v[6:7], 1.0 op_sel_hi:[1,0]
	v_exp_f32_e32 v9, v9
	global_load_dwordx2 v[136:137], v[134:135], off
	v_mul_f32_e32 v10, 0xbfb8aa3b, v10
	v_mul_f32_e32 v11, 0xbfb8aa3b, v11
	v_pk_add_f32 v[8:9], v[8:9], 1.0 op_sel_hi:[1,0]
	v_exp_f32_e32 v10, v10
	v_exp_f32_e32 v11, v11
	s_mov_b32 s2, 0x3fb504f3
	v_mul_f32_e32 v12, 0xbfb8aa3b, v12
	v_mul_f32_e32 v13, 0xbfb8aa3b, v13
	v_pk_add_f32 v[10:11], v[10:11], 1.0 op_sel_hi:[1,0]
	v_exp_f32_e32 v12, v12
	v_exp_f32_e32 v13, v13
	v_mul_f32_e32 v14, 0xbfb8aa3b, v14
	v_mul_f32_e32 v15, 0xbfb8aa3b, v15
	v_exp_f32_e32 v14, v14
	v_pk_add_f32 v[12:13], v[12:13], 1.0 op_sel_hi:[1,0]
	v_exp_f32_e32 v15, v15
	v_mul_f32_e32 v16, 0xbfb8aa3b, v16
	v_mul_f32_e32 v17, 0xbfb8aa3b, v17
	v_exp_f32_e32 v16, v16
	v_pk_add_f32 v[14:15], v[14:15], 1.0 op_sel_hi:[1,0]
	v_exp_f32_e32 v17, v17
	v_mul_f32_e32 v34, 0xbfb8aa3b, v34
	v_mul_f32_e32 v35, 0xbfb8aa3b, v35
	v_exp_f32_e32 v34, v34
	v_pk_add_f32 v[16:17], v[16:17], 1.0 op_sel_hi:[1,0]
	v_exp_f32_e32 v35, v35
	v_mul_f32_e32 v36, 0xbfb8aa3b, v36
	v_mul_f32_e32 v37, 0xbfb8aa3b, v37
	v_exp_f32_e32 v36, v36
	v_pk_add_f32 v[34:35], v[34:35], 1.0 op_sel_hi:[1,0]
	v_exp_f32_e32 v37, v37
	v_mul_f32_e32 v38, 0xbfb8aa3b, v38
	v_mul_f32_e32 v39, 0xbfb8aa3b, v39
	v_exp_f32_e32 v38, v38
	v_pk_add_f32 v[36:37], v[36:37], 1.0 op_sel_hi:[1,0]
	v_exp_f32_e32 v39, v39
	v_mul_f32_e32 v40, 0xbfb8aa3b, v40
	v_mul_f32_e32 v41, 0xbfb8aa3b, v41
	v_exp_f32_e32 v40, v40
	v_pk_add_f32 v[38:39], v[38:39], 1.0 op_sel_hi:[1,0]
	v_exp_f32_e32 v41, v41
	v_mul_f32_e32 v42, 0xbfb8aa3b, v42
	v_mul_f32_e32 v43, 0xbfb8aa3b, v43
	v_exp_f32_e32 v42, v42
	v_pk_add_f32 v[40:41], v[40:41], 1.0 op_sel_hi:[1,0]
	v_exp_f32_e32 v43, v43
	v_mul_f32_e32 v44, 0xbfb8aa3b, v44
	v_mul_f32_e32 v45, 0xbfb8aa3b, v45
	v_exp_f32_e32 v44, v44
	v_pk_add_f32 v[42:43], v[42:43], 1.0 op_sel_hi:[1,0]
	v_exp_f32_e32 v45, v45
	v_mul_f32_e32 v46, 0xbfb8aa3b, v46
	v_mul_f32_e32 v47, 0xbfb8aa3b, v47
	v_exp_f32_e32 v46, v46
	v_pk_add_f32 v[44:45], v[44:45], 1.0 op_sel_hi:[1,0]
	v_exp_f32_e32 v47, v47
	v_mul_f32_e32 v48, 0xbfb8aa3b, v48
	v_mul_f32_e32 v49, 0xbfb8aa3b, v49
	v_exp_f32_e32 v48, v48
	v_pk_add_f32 v[46:47], v[46:47], 1.0 op_sel_hi:[1,0]
	v_exp_f32_e32 v49, v49
	v_mul_f32_e32 v58, 0xbfb8aa3b, v58
	v_mul_f32_e32 v59, 0xbfb8aa3b, v59
	v_exp_f32_e32 v58, v58
	v_pk_add_f32 v[48:49], v[48:49], 1.0 op_sel_hi:[1,0]
	v_exp_f32_e32 v59, v59
	v_mul_f32_e32 v60, 0xbfb8aa3b, v60
	v_mul_f32_e32 v61, 0xbfb8aa3b, v61
	v_exp_f32_e32 v60, v60
	s_waitcnt vmcnt(0)
	v_lshlrev_b32_e32 v131, 16, v142
	v_and_b32_e32 v142, 0xffff0000, v142
	v_rcp_f32_e32 v144, v7
	v_pk_add_f32 v[58:59], v[58:59], 1.0 op_sel_hi:[1,0]
	v_exp_f32_e32 v61, v61
	v_mul_f32_e32 v62, 0xbfb8aa3b, v62
	s_nop 0
	v_mul_f32_e32 v7, v142, v144
	v_rcp_f32_e32 v142, v6
	v_lshlrev_b32_e32 v138, 16, v136
	v_and_b32_e32 v139, 0xffff0000, v136
	v_lshlrev_b32_e32 v136, 16, v137
	s_nop 0
	v_mul_f32_e32 v6, v131, v142
	v_and_b32_e32 v142, 0xffff0000, v143
	v_lshlrev_b32_e32 v131, 16, v143
	v_rcp_f32_e32 v143, v9
	v_and_b32_e32 v137, 0xffff0000, v137
	v_pk_fma_f32 v[6:7], v[138:139], s[2:3], v[6:7] op_sel_hi:[1,0,1]
	v_pk_add_f32 v[60:61], v[60:61], 1.0 op_sel_hi:[1,0]
	s_nop 0
	v_mul_f32_e32 v9, v142, v143
	v_rcp_f32_e32 v142, v8
	v_mul_f32_e32 v63, 0xbfb8aa3b, v63
	v_exp_f32_e32 v62, v62
	v_exp_f32_e32 v63, v63
	s_nop 0
	v_mul_f32_e32 v8, v131, v142
	global_load_dwordx2 v[142:143], v[132:133], off offset:32
	v_pk_fma_f32 v[8:9], v[136:137], s[2:3], v[8:9] op_sel_hi:[1,0,1]
	global_load_dwordx2 v[136:137], v[134:135], off offset:32
	v_pk_add_f32 v[62:63], v[62:63], 1.0 op_sel_hi:[1,0]
	v_mul_f32_e32 v64, 0xbfb8aa3b, v64
	v_mul_f32_e32 v65, 0xbfb8aa3b, v65
	v_exp_f32_e32 v64, v64
	v_exp_f32_e32 v65, v65
	v_mul_f32_e32 v74, 0xbfb8aa3b, v74
	v_mul_f32_e32 v75, 0xbfb8aa3b, v75
	v_exp_f32_e32 v74, v74
	v_pk_add_f32 v[64:65], v[64:65], 1.0 op_sel_hi:[1,0]
	v_exp_f32_e32 v75, v75
	v_mul_f32_e32 v76, 0xbfb8aa3b, v76
	v_mul_f32_e32 v77, 0xbfb8aa3b, v77
	v_exp_f32_e32 v76, v76
	v_pk_add_f32 v[74:75], v[74:75], 1.0 op_sel_hi:[1,0]
	v_exp_f32_e32 v77, v77
	v_mul_f32_e32 v78, 0xbfb8aa3b, v78
	v_mul_f32_e32 v79, 0xbfb8aa3b, v79
	v_exp_f32_e32 v78, v78
	v_pk_add_f32 v[76:77], v[76:77], 1.0 op_sel_hi:[1,0]
	v_exp_f32_e32 v79, v79
	v_mul_f32_e32 v80, 0xbfb8aa3b, v80
	v_mul_f32_e32 v81, 0xbfb8aa3b, v81
	v_exp_f32_e32 v80, v80
	v_pk_add_f32 v[78:79], v[78:79], 1.0 op_sel_hi:[1,0]
	v_exp_f32_e32 v81, v81
	v_mul_f32_e32 v90, 0xbfb8aa3b, v90
	v_mul_f32_e32 v91, 0xbfb8aa3b, v91
	v_exp_f32_e32 v90, v90
	v_pk_add_f32 v[80:81], v[80:81], 1.0 op_sel_hi:[1,0]
	v_exp_f32_e32 v91, v91
	v_mul_f32_e32 v92, 0xbfb8aa3b, v92
	v_mul_f32_e32 v93, 0xbfb8aa3b, v93
	v_exp_f32_e32 v92, v92
	v_pk_add_f32 v[90:91], v[90:91], 1.0 op_sel_hi:[1,0]
	v_exp_f32_e32 v93, v93
	v_mul_f32_e32 v94, 0xbfb8aa3b, v94
	v_mul_f32_e32 v95, 0xbfb8aa3b, v95
;     __device__ __forceinline__ void fused(f32x4 (&acc)[2][2][4][2], const Unit& u, int wr, int wc, int fr, int fq, PG8_LAS unsigned char* lds, int wid, int lane) const {
;     ...
;                     for (int n = 0; n < 2; ++n) { const size_t o = off + bj * HALF + n * 16; const u32x2v xw = *(const u32x2v*)(XR + o); f32x4 a = acc[ai][bj][m][n];
;                         const f32x4 xv = (f32x4){__uint_as_float(xw.x << 16), __uint_as_float(xw.x & 0xffff0000u), __uint_as_float(xw.y << 16), __uint_as_float(xw.y & 0xffff0000u)};
;                         if (MODE == 1) { const u32x2v pw = *(const u32x2v*)(PP + o); const f32x4 pv = (f32x4){__uint_as_float(pw.x << 16), __uint_as_float(pw.x & 0xffff0000u), __uint_as_float(pw.y << 16), __uint_as_float(pw.y & 0xffff0000u)};
; #pragma unroll
;                             for (int j = 0; j < 4; ++j) a[j] = pv[j] / (1.0f + __expf(-a[j])); }
;                         acc[ai][bj][m][n] = xv * DN_ALPHA + a; }
	v_exp_f32_e32 v94, v94
	v_pk_add_f32 v[92:93], v[92:93], 1.0 op_sel_hi:[1,0]
	v_exp_f32_e32 v95, v95
	v_mul_f32_e32 v96, 0xbfb8aa3b, v96
	v_mul_f32_e32 v97, 0xbfb8aa3b, v97
	v_exp_f32_e32 v96, v96
	v_pk_add_f32 v[94:95], v[94:95], 1.0 op_sel_hi:[1,0]
	v_exp_f32_e32 v97, v97
	v_mul_f32_e32 v102, 0xbfb8aa3b, v102
	v_mul_f32_e32 v103, 0xbfb8aa3b, v103
	v_exp_f32_e32 v102, v102
	v_pk_add_f32 v[96:97], v[96:97], 1.0 op_sel_hi:[1,0]
	v_exp_f32_e32 v103, v103
	v_mul_f32_e32 v104, 0xbfb8aa3b, v104
	v_mul_f32_e32 v105, 0xbfb8aa3b, v105
	v_exp_f32_e32 v104, v104
	v_pk_add_f32 v[102:103], v[102:103], 1.0 op_sel_hi:[1,0]
	v_exp_f32_e32 v105, v105
	v_mul_f32_e32 v110, 0xbfb8aa3b, v110
	v_mul_f32_e32 v111, 0xbfb8aa3b, v111
	v_exp_f32_e32 v110, v110
	v_pk_add_f32 v[104:105], v[104:105], 1.0 op_sel_hi:[1,0]
	v_exp_f32_e32 v111, v111
	v_mul_f32_e32 v112, 0xbfb8aa3b, v112
	v_mul_f32_e32 v113, 0xbfb8aa3b, v113
	v_exp_f32_e32 v112, v112
	v_pk_add_f32 v[110:111], v[110:111], 1.0 op_sel_hi:[1,0]
	v_exp_f32_e32 v113, v113
	v_mul_f32_e32 v118, 0xbfb8aa3b, v118
	v_mul_f32_e32 v119, 0xbfb8aa3b, v119
	v_exp_f32_e32 v118, v118
	v_pk_add_f32 v[112:113], v[112:113], 1.0 op_sel_hi:[1,0]
	v_exp_f32_e32 v119, v119
	v_mul_f32_e32 v120, 0xbfb8aa3b, v120
	v_mul_f32_e32 v121, 0xbfb8aa3b, v121
	v_exp_f32_e32 v120, v120
	v_pk_add_f32 v[118:119], v[118:119], 1.0 op_sel_hi:[1,0]
	v_exp_f32_e32 v121, v121
	v_mul_f32_e32 v122, 0xbfb8aa3b, v122
	v_mul_f32_e32 v123, 0xbfb8aa3b, v123
	s_waitcnt vmcnt(1)
	v_lshlrev_b32_e32 v131, 16, v142
	v_and_b32_e32 v142, 0xffff0000, v142
	v_rcp_f32_e32 v144, v11
	s_waitcnt vmcnt(0)
	v_lshlrev_b32_e32 v138, 16, v136
	v_and_b32_e32 v139, 0xffff0000, v136
	v_lshlrev_b32_e32 v136, 16, v137
	s_nop 0
	v_mul_f32_e32 v11, v142, v144
	v_rcp_f32_e32 v142, v10
	v_and_b32_e32 v137, 0xffff0000, v137
	v_pk_add_f32 v[120:121], v[120:121], 1.0 op_sel_hi:[1,0]
	v_exp_f32_e32 v122, v122
	s_nop 0
	v_mul_f32_e32 v10, v131, v142
	v_and_b32_e32 v142, 0xffff0000, v143
	v_lshlrev_b32_e32 v131, 16, v143
	v_rcp_f32_e32 v143, v13
	v_pk_fma_f32 v[10:11], v[138:139], s[2:3], v[10:11] op_sel_hi:[1,0,1]
	v_exp_f32_e32 v123, v123
	v_mul_f32_e32 v124, 0xbfb8aa3b, v124
	s_nop 0
	v_mul_f32_e32 v13, v142, v143
	v_rcp_f32_e32 v142, v12
	v_pk_add_f32 v[122:123], v[122:123], 1.0 op_sel_hi:[1,0]
	v_mul_f32_e32 v125, 0xbfb8aa3b, v125
	v_exp_f32_e32 v124, v124
	s_nop 0
	v_mul_f32_e32 v12, v131, v142
	global_load_dwordx2 v[142:143], v[132:133], off offset:256
	v_pk_fma_f32 v[12:13], v[136:137], s[2:3], v[12:13] op_sel_hi:[1,0,1]
	global_load_dwordx2 v[136:137], v[134:135], off offset:256
	v_exp_f32_e32 v125, v125
	global_load_dwordx2 v[132:133], v[132:133], off offset:288
	v_mul_f32_e32 v126, 0xbfb8aa3b, v126
	v_mul_f32_e32 v127, 0xbfb8aa3b, v127
	v_pk_add_f32 v[124:125], v[124:125], 1.0 op_sel_hi:[1,0]
	v_exp_f32_e32 v126, v126
	v_exp_f32_e32 v127, v127
	v_mul_f32_e32 v128, 0xbfb8aa3b, v128
	v_mul_f32_e32 v129, 0xbfb8aa3b, v129
	v_exp_f32_e32 v128, v128
	v_pk_add_f32 v[126:127], v[126:127], 1.0 op_sel_hi:[1,0]
	v_exp_f32_e32 v129, v129
	v_mul_f32_e32 v114, 0xbfb8aa3b, v114
	v_mul_f32_e32 v115, 0xbfb8aa3b, v115
	v_exp_f32_e32 v114, v114
	v_pk_add_f32 v[128:129], v[128:129], 1.0 op_sel_hi:[1,0]
	v_exp_f32_e32 v115, v115
	v_mul_f32_e32 v116, 0xbfb8aa3b, v116
	v_mul_f32_e32 v117, 0xbfb8aa3b, v117
	v_exp_f32_e32 v116, v116
	v_pk_add_f32 v[114:115], v[114:115], 1.0 op_sel_hi:[1,0]
	v_exp_f32_e32 v117, v117
	v_mul_f32_e32 v106, 0xbfb8aa3b, v106
	v_mul_f32_e32 v107, 0xbfb8aa3b, v107
	v_exp_f32_e32 v106, v106
	v_pk_add_f32 v[116:117], v[116:117], 1.0 op_sel_hi:[1,0]
	v_exp_f32_e32 v107, v107
	v_mul_f32_e32 v108, 0xbfb8aa3b, v108
	v_mul_f32_e32 v109, 0xbfb8aa3b, v109
	v_exp_f32_e32 v108, v108
	v_pk_add_f32 v[106:107], v[106:107], 1.0 op_sel_hi:[1,0]
	v_exp_f32_e32 v109, v109
	v_mul_f32_e32 v98, 0xbfb8aa3b, v98
	v_mul_f32_e32 v99, 0xbfb8aa3b, v99
	v_exp_f32_e32 v98, v98
	v_pk_add_f32 v[108:109], v[108:109], 1.0 op_sel_hi:[1,0]
	v_exp_f32_e32 v99, v99
	v_mul_f32_e32 v100, 0xbfb8aa3b, v100
	v_mul_f32_e32 v101, 0xbfb8aa3b, v101
	v_exp_f32_e32 v100, v100
	v_pk_add_f32 v[98:99], v[98:99], 1.0 op_sel_hi:[1,0]
	v_exp_f32_e32 v101, v101
	v_mul_f32_e32 v86, 0xbfb8aa3b, v86
	v_mul_f32_e32 v87, 0xbfb8aa3b, v87
	v_exp_f32_e32 v86, v86
	v_pk_add_f32 v[100:101], v[100:101], 1.0 op_sel_hi:[1,0]
	v_exp_f32_e32 v87, v87
	v_mul_f32_e32 v88, 0xbfb8aa3b, v88
	v_mul_f32_e32 v89, 0xbfb8aa3b, v89
	v_exp_f32_e32 v88, v88
	v_pk_add_f32 v[86:87], v[86:87], 1.0 op_sel_hi:[1,0]
	v_exp_f32_e32 v89, v89
	v_mul_f32_e32 v82, 0xbfb8aa3b, v82
	v_mul_f32_e32 v83, 0xbfb8aa3b, v83
	v_exp_f32_e32 v82, v82
	v_pk_add_f32 v[88:89], v[88:89], 1.0 op_sel_hi:[1,0]
	v_exp_f32_e32 v83, v83
	v_mul_f32_e32 v84, 0xbfb8aa3b, v84
	v_mul_f32_e32 v85, 0xbfb8aa3b, v85
	v_exp_f32_e32 v84, v84
	v_pk_add_f32 v[82:83], v[82:83], 1.0 op_sel_hi:[1,0]
	v_exp_f32_e32 v85, v85
	v_mul_f32_e32 v70, 0xbfb8aa3b, v70
	v_mul_f32_e32 v71, 0xbfb8aa3b, v71
	v_exp_f32_e32 v70, v70
	v_pk_add_f32 v[84:85], v[84:85], 1.0 op_sel_hi:[1,0]
	v_exp_f32_e32 v71, v71
	v_mul_f32_e32 v72, 0xbfb8aa3b, v72
	v_mul_f32_e32 v73, 0xbfb8aa3b, v73
	v_exp_f32_e32 v72, v72
	v_pk_add_f32 v[70:71], v[70:71], 1.0 op_sel_hi:[1,0]
	v_exp_f32_e32 v73, v73
	v_mul_f32_e32 v66, 0xbfb8aa3b, v66
	v_mul_f32_e32 v67, 0xbfb8aa3b, v67
	v_exp_f32_e32 v66, v66
	v_pk_add_f32 v[72:73], v[72:73], 1.0 op_sel_hi:[1,0]
	v_exp_f32_e32 v67, v67
	s_waitcnt vmcnt(2)
	v_lshlrev_b32_e32 v131, 16, v142
	v_and_b32_e32 v142, 0xffff0000, v142
	v_rcp_f32_e32 v144, v15
	s_waitcnt vmcnt(1)
;     __device__ __forceinline__ void fused(f32x4 (&acc)[2][2][4][2], const Unit& u, int wr, int wc, int fr, int fq, PG8_LAS unsigned char* lds, int wid, int lane) const {
;     ...
;                     for (int n = 0; n < 2; ++n) { const size_t o = off + bj * HALF + n * 16; const u32x2v xw = *(const u32x2v*)(XR + o); f32x4 a = acc[ai][bj][m][n];
;                         const f32x4 xv = (f32x4){__uint_as_float(xw.x << 16), __uint_as_float(xw.x & 0xffff0000u), __uint_as_float(xw.y << 16), __uint_as_float(xw.y & 0xffff0000u)};
;                         if (MODE == 1) { const u32x2v pw = *(const u32x2v*)(PP + o); const f32x4 pv = (f32x4){__uint_as_float(pw.x << 16), __uint_as_float(pw.x & 0xffff0000u), __uint_as_float(pw.y << 16), __uint_as_float(pw.y & 0xffff0000u)};
; #pragma unroll
;                             for (int j = 0; j < 4; ++j) a[j] = pv[j] / (1.0f + __expf(-a[j])); }
;                         acc[ai][bj][m][n] = xv * DN_ALPHA + a; }
	v_lshlrev_b32_e32 v138, 16, v136
	v_and_b32_e32 v139, 0xffff0000, v136
	v_lshlrev_b32_e32 v136, 16, v137
	s_nop 0
	v_mul_f32_e32 v15, v142, v144
	v_rcp_f32_e32 v142, v14
	v_and_b32_e32 v137, 0xffff0000, v137
	v_pk_add_f32 v[66:67], v[66:67], 1.0 op_sel_hi:[1,0]
	v_mul_f32_e32 v68, 0xbfb8aa3b, v68
	s_nop 0
	v_mul_f32_e32 v14, v131, v142
	v_and_b32_e32 v142, 0xffff0000, v143
	v_lshlrev_b32_e32 v131, 16, v143
	v_rcp_f32_e32 v143, v17
	v_pk_fma_f32 v[14:15], v[138:139], s[2:3], v[14:15] op_sel_hi:[1,0,1]
	v_mul_f32_e32 v69, 0xbfb8aa3b, v69
	v_exp_f32_e32 v68, v68
	s_nop 0
	v_mul_f32_e32 v17, v142, v143
	v_rcp_f32_e32 v142, v16
	v_exp_f32_e32 v69, v69
	v_mul_f32_e32 v54, 0xbfb8aa3b, v54
	v_mul_f32_e32 v55, 0xbfb8aa3b, v55
	s_nop 0
	v_mul_f32_e32 v16, v131, v142
	v_pk_fma_f32 v[16:17], v[136:137], s[2:3], v[16:17] op_sel_hi:[1,0,1]
	global_load_dwordx2 v[136:137], v[134:135], off offset:288
	s_waitcnt vmcnt(1)
	v_lshlrev_b32_e32 v131, 16, v132
	v_and_b32_e32 v132, 0xffff0000, v132
	v_rcp_f32_e32 v138, v35
	v_pk_add_f32 v[68:69], v[68:69], 1.0 op_sel_hi:[1,0]
	v_exp_f32_e32 v54, v54
	v_exp_f32_e32 v55, v55
	s_nop 0
	v_mul_f32_e32 v35, v132, v138
	v_rcp_f32_e32 v132, v34
	v_pk_add_f32 v[54:55], v[54:55], 1.0 op_sel_hi:[1,0]
	v_mul_f32_e32 v56, 0xbfb8aa3b, v56
	v_mul_f32_e32 v57, 0xbfb8aa3b, v57
	s_nop 0
	v_mul_f32_e32 v34, v131, v132
	v_and_b32_e32 v132, 0xffff0000, v133
	v_lshlrev_b32_e32 v131, 16, v133
	v_rcp_f32_e32 v133, v37
	v_exp_f32_e32 v56, v56
	v_exp_f32_e32 v57, v57
	v_mul_f32_e32 v50, 0xbfb8aa3b, v50
	s_nop 0
	v_mul_f32_e32 v37, v132, v133
	v_rcp_f32_e32 v132, v36
	v_pk_add_f32 v[56:57], v[56:57], 1.0 op_sel_hi:[1,0]
	v_mul_f32_e32 v51, 0xbfb8aa3b, v51
	v_exp_f32_e32 v50, v50
	s_nop 0
	v_mul_f32_e32 v36, v131, v132
	v_or_b32_e32 v132, 16, v130
	v_ashrrev_i32_e32 v133, 31, v132
	v_lshlrev_b64 v[132:133], 10, v[132:133]
	v_lshl_add_u64 v[132:133], v[132:133], 0, v[162:163]
	v_lshlrev_b64 v[132:133], 1, v[132:133]
	v_exp_f32_e32 v51, v51
	v_mul_f32_e32 v52, 0xbfb8aa3b, v52
	v_mul_f32_e32 v53, 0xbfb8aa3b, v53
	v_exp_f32_e32 v52, v52
	v_pk_add_f32 v[50:51], v[50:51], 1.0 op_sel_hi:[1,0]
	v_exp_f32_e32 v53, v53
	s_waitcnt vmcnt(0)
	v_lshlrev_b32_e32 v134, 16, v136
	v_and_b32_e32 v135, 0xffff0000, v136
	v_lshlrev_b32_e32 v136, 16, v137
	v_and_b32_e32 v137, 0xffff0000, v137
	v_pk_fma_f32 v[36:37], v[136:137], s[2:3], v[36:37] op_sel_hi:[1,0,1]
	v_pk_fma_f32 v[34:35], v[134:135], s[2:3], v[34:35] op_sel_hi:[1,0,1]
	v_lshl_add_u64 v[134:135], s[50:51], 0, v[132:133]
	v_lshl_add_u64 v[132:133], s[52:53], 0, v[132:133]
	global_load_dwordx2 v[142:143], v[132:133], off
	global_load_dwordx2 v[136:137], v[134:135], off
	v_pk_add_f32 v[52:53], v[52:53], 1.0 op_sel_hi:[1,0]
	v_mul_f32_e32 v30, 0xbfb8aa3b, v30
	v_mul_f32_e32 v31, 0xbfb8aa3b, v31
	v_exp_f32_e32 v30, v30
	v_exp_f32_e32 v31, v31
	v_mul_f32_e32 v32, 0xbfb8aa3b, v32
	v_mul_f32_e32 v33, 0xbfb8aa3b, v33
	v_exp_f32_e32 v32, v32
	v_pk_add_f32 v[30:31], v[30:31], 1.0 op_sel_hi:[1,0]
	v_exp_f32_e32 v33, v33
	v_mul_f32_e32 v26, 0xbfb8aa3b, v26
	v_mul_f32_e32 v27, 0xbfb8aa3b, v27
	v_exp_f32_e32 v26, v26
	v_pk_add_f32 v[32:33], v[32:33], 1.0 op_sel_hi:[1,0]
	v_exp_f32_e32 v27, v27
	v_mul_f32_e32 v28, 0xbfb8aa3b, v28
	v_mul_f32_e32 v29, 0xbfb8aa3b, v29
	v_exp_f32_e32 v28, v28
	v_pk_add_f32 v[26:27], v[26:27], 1.0 op_sel_hi:[1,0]
	v_exp_f32_e32 v29, v29
	v_mul_f32_e32 v22, 0xbfb8aa3b, v22
	v_mul_f32_e32 v23, 0xbfb8aa3b, v23
	v_exp_f32_e32 v22, v22
	v_pk_add_f32 v[28:29], v[28:29], 1.0 op_sel_hi:[1,0]
	v_exp_f32_e32 v23, v23
	v_mul_f32_e32 v24, 0xbfb8aa3b, v24
	v_mul_f32_e32 v25, 0xbfb8aa3b, v25
	v_exp_f32_e32 v24, v24
	v_pk_add_f32 v[22:23], v[22:23], 1.0 op_sel_hi:[1,0]
	v_exp_f32_e32 v25, v25
	v_mul_f32_e32 v18, 0xbfb8aa3b, v18
	v_mul_f32_e32 v19, 0xbfb8aa3b, v19
	v_exp_f32_e32 v18, v18
	v_pk_add_f32 v[24:25], v[24:25], 1.0 op_sel_hi:[1,0]
	v_exp_f32_e32 v19, v19
	v_mul_f32_e32 v20, 0xbfb8aa3b, v20
	v_mul_f32_e32 v21, 0xbfb8aa3b, v21
	v_exp_f32_e32 v20, v20
	v_pk_add_f32 v[18:19], v[18:19], 1.0 op_sel_hi:[1,0]
	v_exp_f32_e32 v21, v21
	v_mul_f32_e32 v2, 0xbfb8aa3b, v2
	v_mul_f32_e32 v3, 0xbfb8aa3b, v3
	v_exp_f32_e32 v2, v2
	v_pk_add_f32 v[20:21], v[20:21], 1.0 op_sel_hi:[1,0]
	v_exp_f32_e32 v3, v3
	v_mul_f32_e32 v4, 0xbfb8aa3b, v4
	v_mul_f32_e32 v5, 0xbfb8aa3b, v5
	v_exp_f32_e32 v4, v4
	v_pk_add_f32 v[2:3], v[2:3], 1.0 op_sel_hi:[1,0]
	v_exp_f32_e32 v5, v5
	v_and_b32_e32 v0, 63, v140
	v_pk_add_f32 v[4:5], v[4:5], 1.0 op_sel_hi:[1,0]
	s_waitcnt vmcnt(1)
	v_lshlrev_b32_e32 v131, 16, v142
	v_and_b32_e32 v142, 0xffff0000, v142
	v_rcp_f32_e32 v144, v39
	s_waitcnt vmcnt(0)
	v_lshlrev_b32_e32 v138, 16, v136
	v_and_b32_e32 v139, 0xffff0000, v136
	v_lshlrev_b32_e32 v136, 16, v137
	s_nop 0
	v_mul_f32_e32 v39, v142, v144
	v_rcp_f32_e32 v142, v38
	v_and_b32_e32 v137, 0xffff0000, v137
	s_nop 0
	v_mul_f32_e32 v38, v131, v142
	v_and_b32_e32 v142, 0xffff0000, v143
	v_lshlrev_b32_e32 v131, 16, v143
	v_rcp_f32_e32 v143, v41
	v_pk_fma_f32 v[38:39], v[138:139], s[2:3], v[38:39] op_sel_hi:[1,0,1]
	s_nop 0
	v_mul_f32_e32 v41, v142, v143
	v_rcp_f32_e32 v142, v40
	s_nop 0
	s_nop 0
	v_mul_f32_e32 v40, v131, v142
	global_load_dwordx2 v[142:143], v[132:133], off offset:32
	v_pk_fma_f32 v[40:41], v[136:137], s[2:3], v[40:41] op_sel_hi:[1,0,1]
	global_load_dwordx2 v[136:137], v[134:135], off offset:32
	s_waitcnt vmcnt(1)
	v_lshlrev_b32_e32 v131, 16, v142
	v_and_b32_e32 v142, 0xffff0000, v142
	v_rcp_f32_e32 v144, v43
	s_waitcnt vmcnt(0)
;     __device__ __forceinline__ void fused(f32x4 (&acc)[2][2][4][2], const Unit& u, int wr, int wc, int fr, int fq, PG8_LAS unsigned char* lds, int wid, int lane) const {
;     ...
;                     for (int n = 0; n < 2; ++n) { const size_t o = off + bj * HALF + n * 16; const u32x2v xw = *(const u32x2v*)(XR + o); f32x4 a = acc[ai][bj][m][n];
;                         const f32x4 xv = (f32x4){__uint_as_float(xw.x << 16), __uint_as_float(xw.x & 0xffff0000u), __uint_as_float(xw.y << 16), __uint_as_float(xw.y & 0xffff0000u)};
;                         if (MODE == 1) { const u32x2v pw = *(const u32x2v*)(PP + o); const f32x4 pv = (f32x4){__uint_as_float(pw.x << 16), __uint_as_float(pw.x & 0xffff0000u), __uint_as_float(pw.y << 16), __uint_as_float(pw.y & 0xffff0000u)};
; #pragma unroll
;                             for (int j = 0; j < 4; ++j) a[j] = pv[j] / (1.0f + __expf(-a[j])); }
;                         acc[ai][bj][m][n] = xv * DN_ALPHA + a; }
	v_lshlrev_b32_e32 v138, 16, v136
	v_and_b32_e32 v139, 0xffff0000, v136
	v_lshlrev_b32_e32 v136, 16, v137
	s_nop 0
	v_mul_f32_e32 v43, v142, v144
	v_rcp_f32_e32 v142, v42
	v_and_b32_e32 v137, 0xffff0000, v137
	s_nop 0
	v_mul_f32_e32 v42, v131, v142
	v_and_b32_e32 v142, 0xffff0000, v143
	v_lshlrev_b32_e32 v131, 16, v143
	v_rcp_f32_e32 v143, v45
	v_pk_fma_f32 v[42:43], v[138:139], s[2:3], v[42:43] op_sel_hi:[1,0,1]
	s_nop 0
	v_mul_f32_e32 v45, v142, v143
	v_rcp_f32_e32 v142, v44
	s_nop 0
	s_nop 0
	v_mul_f32_e32 v44, v131, v142
	global_load_dwordx2 v[142:143], v[132:133], off offset:256
	v_pk_fma_f32 v[44:45], v[136:137], s[2:3], v[44:45] op_sel_hi:[1,0,1]
	global_load_dwordx2 v[136:137], v[134:135], off offset:256
	s_waitcnt vmcnt(1)
	v_lshlrev_b32_e32 v131, 16, v142
	global_load_dwordx2 v[132:133], v[132:133], off offset:288
	v_and_b32_e32 v142, 0xffff0000, v142
	v_rcp_f32_e32 v144, v47
	s_waitcnt vmcnt(1)
	v_lshlrev_b32_e32 v138, 16, v136
	v_and_b32_e32 v139, 0xffff0000, v136
	v_lshlrev_b32_e32 v136, 16, v137
	s_nop 0
	v_mul_f32_e32 v47, v142, v144
	v_rcp_f32_e32 v142, v46
	v_and_b32_e32 v137, 0xffff0000, v137
	s_nop 0
	v_mul_f32_e32 v46, v131, v142
	v_and_b32_e32 v142, 0xffff0000, v143
	v_lshlrev_b32_e32 v131, 16, v143
	v_rcp_f32_e32 v143, v49
	v_pk_fma_f32 v[46:47], v[138:139], s[2:3], v[46:47] op_sel_hi:[1,0,1]
	s_nop 0
	v_mul_f32_e32 v49, v142, v143
	v_rcp_f32_e32 v142, v48
	s_nop 0
	s_nop 0
	v_mul_f32_e32 v48, v131, v142
	v_pk_fma_f32 v[48:49], v[136:137], s[2:3], v[48:49] op_sel_hi:[1,0,1]
	global_load_dwordx2 v[136:137], v[134:135], off offset:288
	s_waitcnt vmcnt(1)
	v_lshlrev_b32_e32 v131, 16, v132
	v_and_b32_e32 v132, 0xffff0000, v132
	v_rcp_f32_e32 v138, v59
	s_waitcnt vmcnt(0)
	v_lshlrev_b32_e32 v134, 16, v136
	s_nop 0
	v_mul_f32_e32 v59, v132, v138
	v_rcp_f32_e32 v132, v58
	v_and_b32_e32 v135, 0xffff0000, v136
	v_lshlrev_b32_e32 v136, 16, v137
	v_and_b32_e32 v137, 0xffff0000, v137
	s_nop 0
	v_mul_f32_e32 v58, v131, v132
	v_and_b32_e32 v132, 0xffff0000, v133
	v_lshlrev_b32_e32 v131, 16, v133
	v_rcp_f32_e32 v133, v61
	v_pk_fma_f32 v[58:59], v[134:135], s[2:3], v[58:59] op_sel_hi:[1,0,1]
	s_nop 0
	v_mul_f32_e32 v61, v132, v133
	v_rcp_f32_e32 v132, v60
	s_nop 0
	s_nop 0
	v_mul_f32_e32 v60, v131, v132
	v_or_b32_e32 v132, 32, v130
	v_ashrrev_i32_e32 v133, 31, v132
	v_lshlrev_b64 v[132:133], 10, v[132:133]
	v_lshl_add_u64 v[132:133], v[132:133], 0, v[162:163]
	v_pk_fma_f32 v[60:61], v[136:137], s[2:3], v[60:61] op_sel_hi:[1,0,1]
	v_lshlrev_b64 v[132:133], 1, v[132:133]
	v_lshl_add_u64 v[134:135], s[50:51], 0, v[132:133]
	v_lshl_add_u64 v[132:133], s[52:53], 0, v[132:133]
	global_load_dwordx2 v[142:143], v[132:133], off
	global_load_dwordx2 v[136:137], v[134:135], off
	s_waitcnt vmcnt(1)
	v_lshlrev_b32_e32 v131, 16, v142
	v_and_b32_e32 v142, 0xffff0000, v142
	v_rcp_f32_e32 v144, v63
	s_waitcnt vmcnt(0)
	v_lshlrev_b32_e32 v138, 16, v136
	v_and_b32_e32 v139, 0xffff0000, v136
	v_lshlrev_b32_e32 v136, 16, v137
	s_nop 0
	v_mul_f32_e32 v63, v142, v144
	v_rcp_f32_e32 v142, v62
	v_and_b32_e32 v137, 0xffff0000, v137
	s_nop 0
	v_mul_f32_e32 v62, v131, v142
	v_and_b32_e32 v142, 0xffff0000, v143
	v_lshlrev_b32_e32 v131, 16, v143
	v_rcp_f32_e32 v143, v65
	v_pk_fma_f32 v[62:63], v[138:139], s[2:3], v[62:63] op_sel_hi:[1,0,1]
	s_nop 0
	v_mul_f32_e32 v65, v142, v143
	v_rcp_f32_e32 v142, v64
	s_nop 0
	s_nop 0
	v_mul_f32_e32 v64, v131, v142
	global_load_dwordx2 v[142:143], v[132:133], off offset:32
	v_pk_fma_f32 v[64:65], v[136:137], s[2:3], v[64:65] op_sel_hi:[1,0,1]
	global_load_dwordx2 v[136:137], v[134:135], off offset:32
	s_waitcnt vmcnt(1)
	v_lshlrev_b32_e32 v131, 16, v142
	v_and_b32_e32 v142, 0xffff0000, v142
	v_rcp_f32_e32 v144, v75
	s_waitcnt vmcnt(0)
	v_lshlrev_b32_e32 v138, 16, v136
	v_and_b32_e32 v139, 0xffff0000, v136
	v_lshlrev_b32_e32 v136, 16, v137
	s_nop 0
	v_mul_f32_e32 v75, v142, v144
	v_rcp_f32_e32 v142, v74
	v_and_b32_e32 v137, 0xffff0000, v137
	s_nop 0
	v_mul_f32_e32 v74, v131, v142
	v_and_b32_e32 v142, 0xffff0000, v143
	v_lshlrev_b32_e32 v131, 16, v143
	v_rcp_f32_e32 v143, v77
	v_pk_fma_f32 v[74:75], v[138:139], s[2:3], v[74:75] op_sel_hi:[1,0,1]
	s_nop 0
	v_mul_f32_e32 v77, v142, v143
	v_rcp_f32_e32 v142, v76
	s_nop 0
	s_nop 0
	v_mul_f32_e32 v76, v131, v142
	global_load_dwordx2 v[142:143], v[132:133], off offset:256
	v_pk_fma_f32 v[76:77], v[136:137], s[2:3], v[76:77] op_sel_hi:[1,0,1]
	global_load_dwordx2 v[136:137], v[134:135], off offset:256
	s_waitcnt vmcnt(1)
	v_lshlrev_b32_e32 v131, 16, v142
	global_load_dwordx2 v[132:133], v[132:133], off offset:288
	v_and_b32_e32 v142, 0xffff0000, v142
	v_rcp_f32_e32 v144, v79
	s_waitcnt vmcnt(1)
	v_lshlrev_b32_e32 v138, 16, v136
	v_and_b32_e32 v139, 0xffff0000, v136
	v_lshlrev_b32_e32 v136, 16, v137
	s_nop 0
	v_mul_f32_e32 v79, v142, v144
	v_rcp_f32_e32 v142, v78
	v_and_b32_e32 v137, 0xffff0000, v137
	s_nop 0
	v_mul_f32_e32 v78, v131, v142
	v_and_b32_e32 v142, 0xffff0000, v143
	v_lshlrev_b32_e32 v131, 16, v143
	v_rcp_f32_e32 v143, v81
	v_pk_fma_f32 v[78:79], v[138:139], s[2:3], v[78:79] op_sel_hi:[1,0,1]
	s_nop 0
	v_mul_f32_e32 v81, v142, v143
	v_rcp_f32_e32 v142, v80
	s_nop 0
	s_nop 0
	v_mul_f32_e32 v80, v131, v142
	v_pk_fma_f32 v[80:81], v[136:137], s[2:3], v[80:81] op_sel_hi:[1,0,1]
	global_load_dwordx2 v[136:137], v[134:135], off offset:288
	s_waitcnt vmcnt(1)
	v_lshlrev_b32_e32 v131, 16, v132
	v_and_b32_e32 v132, 0xffff0000, v132
	v_rcp_f32_e32 v138, v91
	s_waitcnt vmcnt(0)
;     __device__ __forceinline__ void fused(f32x4 (&acc)[2][2][4][2], const Unit& u, int wr, int wc, int fr, int fq, PG8_LAS unsigned char* lds, int wid, int lane) const {
;     ...
;                     for (int n = 0; n < 2; ++n) { const size_t o = off + bj * HALF + n * 16; const u32x2v xw = *(const u32x2v*)(XR + o); f32x4 a = acc[ai][bj][m][n];
;                         const f32x4 xv = (f32x4){__uint_as_float(xw.x << 16), __uint_as_float(xw.x & 0xffff0000u), __uint_as_float(xw.y << 16), __uint_as_float(xw.y & 0xffff0000u)};
;                         if (MODE == 1) { const u32x2v pw = *(const u32x2v*)(PP + o); const f32x4 pv = (f32x4){__uint_as_float(pw.x << 16), __uint_as_float(pw.x & 0xffff0000u), __uint_as_float(pw.y << 16), __uint_as_float(pw.y & 0xffff0000u)};
; #pragma unroll
;                             for (int j = 0; j < 4; ++j) a[j] = pv[j] / (1.0f + __expf(-a[j])); }
;                         acc[ai][bj][m][n] = xv * DN_ALPHA + a; }
	v_lshlrev_b32_e32 v134, 16, v136
	s_nop 0
	v_mul_f32_e32 v91, v132, v138
	v_rcp_f32_e32 v132, v90
	v_and_b32_e32 v135, 0xffff0000, v136
	v_lshlrev_b32_e32 v136, 16, v137
	v_and_b32_e32 v137, 0xffff0000, v137
	s_nop 0
	v_mul_f32_e32 v90, v131, v132
	v_and_b32_e32 v132, 0xffff0000, v133
	v_lshlrev_b32_e32 v131, 16, v133
	v_rcp_f32_e32 v133, v93
	v_pk_fma_f32 v[90:91], v[134:135], s[2:3], v[90:91] op_sel_hi:[1,0,1]
	s_nop 0
	v_mul_f32_e32 v93, v132, v133
	v_rcp_f32_e32 v132, v92
	s_nop 0
	s_nop 0
	v_mul_f32_e32 v92, v131, v132
	v_or_b32_e32 v132, 48, v130
	v_ashrrev_i32_e32 v133, 31, v132
	v_lshlrev_b64 v[132:133], 10, v[132:133]
	v_lshl_add_u64 v[132:133], v[132:133], 0, v[162:163]
	v_lshlrev_b64 v[132:133], 1, v[132:133]
	v_pk_fma_f32 v[92:93], v[136:137], s[2:3], v[92:93] op_sel_hi:[1,0,1]
	v_lshl_add_u64 v[134:135], s[50:51], 0, v[132:133]
	v_lshl_add_u64 v[132:133], s[52:53], 0, v[132:133]
	global_load_dwordx2 v[142:143], v[132:133], off
	global_load_dwordx2 v[136:137], v[134:135], off
	s_waitcnt vmcnt(1)
	v_lshlrev_b32_e32 v131, 16, v142
	v_and_b32_e32 v142, 0xffff0000, v142
	v_rcp_f32_e32 v144, v95
	s_waitcnt vmcnt(0)
	v_lshlrev_b32_e32 v138, 16, v136
	v_and_b32_e32 v139, 0xffff0000, v136
	v_lshlrev_b32_e32 v136, 16, v137
	s_nop 0
	v_mul_f32_e32 v95, v142, v144
	v_rcp_f32_e32 v142, v94
	v_and_b32_e32 v137, 0xffff0000, v137
	s_nop 0
	v_mul_f32_e32 v94, v131, v142
	v_and_b32_e32 v142, 0xffff0000, v143
	v_lshlrev_b32_e32 v131, 16, v143
	v_rcp_f32_e32 v143, v97
	v_pk_fma_f32 v[94:95], v[138:139], s[2:3], v[94:95] op_sel_hi:[1,0,1]
	s_nop 0
	v_mul_f32_e32 v97, v142, v143
	v_rcp_f32_e32 v142, v96
	s_nop 0
	s_nop 0
	v_mul_f32_e32 v96, v131, v142
	global_load_dwordx2 v[142:143], v[132:133], off offset:32
	v_pk_fma_f32 v[96:97], v[136:137], s[2:3], v[96:97] op_sel_hi:[1,0,1]
	global_load_dwordx2 v[136:137], v[134:135], off offset:32
	s_waitcnt vmcnt(1)
	v_lshlrev_b32_e32 v131, 16, v142
	v_and_b32_e32 v142, 0xffff0000, v142
	v_rcp_f32_e32 v144, v103
	s_waitcnt vmcnt(0)
	v_lshlrev_b32_e32 v138, 16, v136
	v_and_b32_e32 v139, 0xffff0000, v136
	v_lshlrev_b32_e32 v136, 16, v137
	s_nop 0
	v_mul_f32_e32 v103, v142, v144
	v_rcp_f32_e32 v142, v102
	v_and_b32_e32 v137, 0xffff0000, v137
	s_nop 0
	v_mul_f32_e32 v102, v131, v142
	v_and_b32_e32 v142, 0xffff0000, v143
	v_lshlrev_b32_e32 v131, 16, v143
	v_rcp_f32_e32 v143, v105
	v_pk_fma_f32 v[102:103], v[138:139], s[2:3], v[102:103] op_sel_hi:[1,0,1]
	s_nop 0
	v_mul_f32_e32 v105, v142, v143
	v_rcp_f32_e32 v142, v104
	s_nop 0
	s_nop 0
	v_mul_f32_e32 v104, v131, v142
	global_load_dwordx2 v[142:143], v[132:133], off offset:256
	v_pk_fma_f32 v[104:105], v[136:137], s[2:3], v[104:105] op_sel_hi:[1,0,1]
	global_load_dwordx2 v[136:137], v[134:135], off offset:256
	s_waitcnt vmcnt(1)
	v_lshlrev_b32_e32 v131, 16, v142
	global_load_dwordx2 v[132:133], v[132:133], off offset:288
	v_and_b32_e32 v142, 0xffff0000, v142
	v_rcp_f32_e32 v144, v111
	s_waitcnt vmcnt(1)
	v_lshlrev_b32_e32 v138, 16, v136
	v_and_b32_e32 v139, 0xffff0000, v136
	v_lshlrev_b32_e32 v136, 16, v137
	s_nop 0
	v_mul_f32_e32 v111, v142, v144
	v_rcp_f32_e32 v142, v110
	v_and_b32_e32 v137, 0xffff0000, v137
	s_nop 0
	v_mul_f32_e32 v110, v131, v142
	v_and_b32_e32 v142, 0xffff0000, v143
	v_lshlrev_b32_e32 v131, 16, v143
	v_rcp_f32_e32 v143, v113
	v_pk_fma_f32 v[110:111], v[138:139], s[2:3], v[110:111] op_sel_hi:[1,0,1]
	s_nop 0
	v_mul_f32_e32 v113, v142, v143
	v_rcp_f32_e32 v142, v112
	s_nop 0
	s_nop 0
	v_mul_f32_e32 v112, v131, v142
	v_pk_fma_f32 v[112:113], v[136:137], s[2:3], v[112:113] op_sel_hi:[1,0,1]
	global_load_dwordx2 v[136:137], v[134:135], off offset:288
	s_waitcnt vmcnt(1)
	v_lshlrev_b32_e32 v131, 16, v132
	v_and_b32_e32 v132, 0xffff0000, v132
	v_rcp_f32_e32 v138, v119
	s_waitcnt vmcnt(0)
	v_lshlrev_b32_e32 v134, 16, v136
	s_nop 0
	v_mul_f32_e32 v119, v132, v138
	v_rcp_f32_e32 v132, v118
	v_and_b32_e32 v135, 0xffff0000, v136
	v_lshlrev_b32_e32 v136, 16, v137
	v_and_b32_e32 v137, 0xffff0000, v137
	s_nop 0
	v_mul_f32_e32 v118, v131, v132
	v_and_b32_e32 v132, 0xffff0000, v133
	v_lshlrev_b32_e32 v131, 16, v133
	v_rcp_f32_e32 v133, v121
	v_pk_fma_f32 v[118:119], v[134:135], s[2:3], v[118:119] op_sel_hi:[1,0,1]
	s_nop 0
	v_mul_f32_e32 v121, v132, v133
	v_rcp_f32_e32 v132, v120
	s_nop 0
	s_nop 0
	v_mul_f32_e32 v120, v131, v132
	v_add_u32_e32 v132, 0x80, v130
	v_ashrrev_i32_e32 v133, 31, v132
	v_lshlrev_b64 v[132:133], 10, v[132:133]
	v_lshl_add_u64 v[132:133], v[132:133], 0, v[162:163]
	v_pk_fma_f32 v[120:121], v[136:137], s[2:3], v[120:121] op_sel_hi:[1,0,1]
	v_lshlrev_b64 v[132:133], 1, v[132:133]
	v_lshl_add_u64 v[134:135], s[50:51], 0, v[132:133]
	v_lshl_add_u64 v[132:133], s[52:53], 0, v[132:133]
	global_load_dwordx2 v[142:143], v[132:133], off
	global_load_dwordx2 v[136:137], v[134:135], off
	s_waitcnt vmcnt(1)
	v_lshlrev_b32_e32 v131, 16, v142
	v_and_b32_e32 v142, 0xffff0000, v142
	v_rcp_f32_e32 v144, v123
	s_waitcnt vmcnt(0)
	v_lshlrev_b32_e32 v138, 16, v136
	v_and_b32_e32 v139, 0xffff0000, v136
	v_lshlrev_b32_e32 v136, 16, v137
	s_nop 0
	v_mul_f32_e32 v123, v142, v144
	v_rcp_f32_e32 v142, v122
	v_and_b32_e32 v137, 0xffff0000, v137
	s_nop 0
	v_mul_f32_e32 v122, v131, v142
	v_and_b32_e32 v142, 0xffff0000, v143
	v_lshlrev_b32_e32 v131, 16, v143
	v_rcp_f32_e32 v143, v125
	v_pk_fma_f32 v[122:123], v[138:139], s[2:3], v[122:123] op_sel_hi:[1,0,1]
	s_nop 0
	v_mul_f32_e32 v125, v142, v143
	v_rcp_f32_e32 v142, v124
	s_nop 0
	s_nop 0
	v_mul_f32_e32 v124, v131, v142
	global_load_dwordx2 v[142:143], v[132:133], off offset:32
	v_pk_fma_f32 v[124:125], v[136:137], s[2:3], v[124:125] op_sel_hi:[1,0,1]
	global_load_dwordx2 v[136:137], v[134:135], off offset:32
	s_waitcnt vmcnt(1)
;     __device__ __forceinline__ void fused(f32x4 (&acc)[2][2][4][2], const Unit& u, int wr, int wc, int fr, int fq, PG8_LAS unsigned char* lds, int wid, int lane) const {
;     ...
;                     for (int n = 0; n < 2; ++n) { const size_t o = off + bj * HALF + n * 16; const u32x2v xw = *(const u32x2v*)(XR + o); f32x4 a = acc[ai][bj][m][n];
;                         const f32x4 xv = (f32x4){__uint_as_float(xw.x << 16), __uint_as_float(xw.x & 0xffff0000u), __uint_as_float(xw.y << 16), __uint_as_float(xw.y & 0xffff0000u)};
;                         if (MODE == 1) { const u32x2v pw = *(const u32x2v*)(PP + o); const f32x4 pv = (f32x4){__uint_as_float(pw.x << 16), __uint_as_float(pw.x & 0xffff0000u), __uint_as_float(pw.y << 16), __uint_as_float(pw.y & 0xffff0000u)};
; #pragma unroll
;                             for (int j = 0; j < 4; ++j) a[j] = pv[j] / (1.0f + __expf(-a[j])); }
;                         acc[ai][bj][m][n] = xv * DN_ALPHA + a; }
	v_lshlrev_b32_e32 v131, 16, v142
	v_and_b32_e32 v142, 0xffff0000, v142
	v_rcp_f32_e32 v144, v127
	s_waitcnt vmcnt(0)
	v_lshlrev_b32_e32 v138, 16, v136
	v_and_b32_e32 v139, 0xffff0000, v136
	v_lshlrev_b32_e32 v136, 16, v137
	s_nop 0
	v_mul_f32_e32 v127, v142, v144
	v_rcp_f32_e32 v142, v126
	v_and_b32_e32 v137, 0xffff0000, v137
	s_nop 0
	v_mul_f32_e32 v126, v131, v142
	v_and_b32_e32 v142, 0xffff0000, v143
	v_lshlrev_b32_e32 v131, 16, v143
	v_rcp_f32_e32 v143, v129
	v_pk_fma_f32 v[126:127], v[138:139], s[2:3], v[126:127] op_sel_hi:[1,0,1]
	s_nop 0
	v_mul_f32_e32 v129, v142, v143
	v_rcp_f32_e32 v142, v128
	s_nop 0
	s_nop 0
	v_mul_f32_e32 v128, v131, v142
	global_load_dwordx2 v[142:143], v[132:133], off offset:256
	v_pk_fma_f32 v[128:129], v[136:137], s[2:3], v[128:129] op_sel_hi:[1,0,1]
	global_load_dwordx2 v[136:137], v[134:135], off offset:256
	s_waitcnt vmcnt(1)
	v_lshlrev_b32_e32 v131, 16, v142
	global_load_dwordx2 v[132:133], v[132:133], off offset:288
	v_and_b32_e32 v142, 0xffff0000, v142
	v_rcp_f32_e32 v144, v115
	s_waitcnt vmcnt(1)
	v_lshlrev_b32_e32 v138, 16, v136
	v_and_b32_e32 v139, 0xffff0000, v136
	v_lshlrev_b32_e32 v136, 16, v137
	s_nop 0
	v_mul_f32_e32 v115, v142, v144
	v_rcp_f32_e32 v142, v114
	v_and_b32_e32 v137, 0xffff0000, v137
	s_nop 0
	v_mul_f32_e32 v114, v131, v142
	v_and_b32_e32 v142, 0xffff0000, v143
	v_lshlrev_b32_e32 v131, 16, v143
	v_rcp_f32_e32 v143, v117
	v_pk_fma_f32 v[114:115], v[138:139], s[2:3], v[114:115] op_sel_hi:[1,0,1]
	s_nop 0
	v_mul_f32_e32 v117, v142, v143
	v_rcp_f32_e32 v142, v116
	s_nop 0
	s_nop 0
	v_mul_f32_e32 v116, v131, v142
	v_pk_fma_f32 v[116:117], v[136:137], s[2:3], v[116:117] op_sel_hi:[1,0,1]
	global_load_dwordx2 v[136:137], v[134:135], off offset:288
	s_waitcnt vmcnt(1)
	v_lshlrev_b32_e32 v131, 16, v132
	v_and_b32_e32 v132, 0xffff0000, v132
	v_rcp_f32_e32 v138, v107
	s_waitcnt vmcnt(0)
	v_lshlrev_b32_e32 v134, 16, v136
	s_nop 0
	v_mul_f32_e32 v107, v132, v138
	v_rcp_f32_e32 v132, v106
	v_and_b32_e32 v135, 0xffff0000, v136
	v_lshlrev_b32_e32 v136, 16, v137
	v_and_b32_e32 v137, 0xffff0000, v137
	s_nop 0
	v_mul_f32_e32 v106, v131, v132
	v_and_b32_e32 v132, 0xffff0000, v133
	v_lshlrev_b32_e32 v131, 16, v133
	v_rcp_f32_e32 v133, v109
	v_pk_fma_f32 v[106:107], v[134:135], s[2:3], v[106:107] op_sel_hi:[1,0,1]
	s_nop 0
	v_mul_f32_e32 v109, v132, v133
	v_rcp_f32_e32 v132, v108
	s_nop 0
	s_nop 0
	v_mul_f32_e32 v108, v131, v132
	v_add_u32_e32 v132, 0x90, v130
	v_ashrrev_i32_e32 v133, 31, v132
	v_lshlrev_b64 v[132:133], 10, v[132:133]
	v_lshl_add_u64 v[132:133], v[132:133], 0, v[162:163]
	v_lshlrev_b64 v[132:133], 1, v[132:133]
	v_pk_fma_f32 v[108:109], v[136:137], s[2:3], v[108:109] op_sel_hi:[1,0,1]
	v_lshl_add_u64 v[134:135], s[50:51], 0, v[132:133]
	v_lshl_add_u64 v[132:133], s[52:53], 0, v[132:133]
	global_load_dwordx2 v[142:143], v[132:133], off
	global_load_dwordx2 v[136:137], v[134:135], off
	s_waitcnt vmcnt(1)
	v_lshlrev_b32_e32 v131, 16, v142
	v_and_b32_e32 v142, 0xffff0000, v142
	v_rcp_f32_e32 v144, v99
	s_waitcnt vmcnt(0)
	v_lshlrev_b32_e32 v138, 16, v136
	v_and_b32_e32 v139, 0xffff0000, v136
	v_lshlrev_b32_e32 v136, 16, v137
	s_nop 0
	v_mul_f32_e32 v99, v142, v144
	v_rcp_f32_e32 v142, v98
	v_and_b32_e32 v137, 0xffff0000, v137
	s_nop 0
	v_mul_f32_e32 v98, v131, v142
	v_and_b32_e32 v142, 0xffff0000, v143
	v_lshlrev_b32_e32 v131, 16, v143
	v_rcp_f32_e32 v143, v101
	v_pk_fma_f32 v[98:99], v[138:139], s[2:3], v[98:99] op_sel_hi:[1,0,1]
	s_nop 0
	v_mul_f32_e32 v101, v142, v143
	v_rcp_f32_e32 v142, v100
	s_nop 0
	s_nop 0
	v_mul_f32_e32 v100, v131, v142
	global_load_dwordx2 v[142:143], v[132:133], off offset:32
	v_pk_fma_f32 v[100:101], v[136:137], s[2:3], v[100:101] op_sel_hi:[1,0,1]
	global_load_dwordx2 v[136:137], v[134:135], off offset:32
	s_waitcnt vmcnt(1)
	v_lshlrev_b32_e32 v131, 16, v142
	v_and_b32_e32 v142, 0xffff0000, v142
	v_rcp_f32_e32 v144, v87
	s_waitcnt vmcnt(0)
	v_lshlrev_b32_e32 v138, 16, v136
	v_and_b32_e32 v139, 0xffff0000, v136
	v_lshlrev_b32_e32 v136, 16, v137
	s_nop 0
	v_mul_f32_e32 v87, v142, v144
	v_rcp_f32_e32 v142, v86
	v_and_b32_e32 v137, 0xffff0000, v137
	s_nop 0
	v_mul_f32_e32 v86, v131, v142
	v_and_b32_e32 v142, 0xffff0000, v143
	v_lshlrev_b32_e32 v131, 16, v143
	v_rcp_f32_e32 v143, v89
	v_pk_fma_f32 v[86:87], v[138:139], s[2:3], v[86:87] op_sel_hi:[1,0,1]
	s_nop 0
	v_mul_f32_e32 v89, v142, v143
	v_rcp_f32_e32 v142, v88
	s_nop 0
	s_nop 0
	v_mul_f32_e32 v88, v131, v142
	global_load_dwordx2 v[142:143], v[132:133], off offset:256
	v_pk_fma_f32 v[88:89], v[136:137], s[2:3], v[88:89] op_sel_hi:[1,0,1]
	global_load_dwordx2 v[136:137], v[134:135], off offset:256
	s_waitcnt vmcnt(1)
	v_lshlrev_b32_e32 v131, 16, v142
	global_load_dwordx2 v[132:133], v[132:133], off offset:288
	v_and_b32_e32 v142, 0xffff0000, v142
	v_rcp_f32_e32 v144, v83
	s_waitcnt vmcnt(1)
	v_lshlrev_b32_e32 v138, 16, v136
	v_and_b32_e32 v139, 0xffff0000, v136
	v_lshlrev_b32_e32 v136, 16, v137
	s_nop 0
	v_mul_f32_e32 v83, v142, v144
	v_rcp_f32_e32 v142, v82
	v_and_b32_e32 v137, 0xffff0000, v137
	s_nop 0
	v_mul_f32_e32 v82, v131, v142
	v_and_b32_e32 v142, 0xffff0000, v143
	v_lshlrev_b32_e32 v131, 16, v143
	v_rcp_f32_e32 v143, v85
	v_pk_fma_f32 v[82:83], v[138:139], s[2:3], v[82:83] op_sel_hi:[1,0,1]
	s_nop 0
	v_mul_f32_e32 v85, v142, v143
	v_rcp_f32_e32 v142, v84
	s_nop 0
	s_nop 0
	v_mul_f32_e32 v84, v131, v142
	v_pk_fma_f32 v[84:85], v[136:137], s[2:3], v[84:85] op_sel_hi:[1,0,1]
	global_load_dwordx2 v[136:137], v[134:135], off offset:288
	s_waitcnt vmcnt(1)
	v_lshlrev_b32_e32 v131, 16, v132
	v_and_b32_e32 v132, 0xffff0000, v132
	v_rcp_f32_e32 v138, v71
	s_waitcnt vmcnt(0)
;     __device__ __forceinline__ void fused(f32x4 (&acc)[2][2][4][2], const Unit& u, int wr, int wc, int fr, int fq, PG8_LAS unsigned char* lds, int wid, int lane) const {
;     ...
;                     for (int n = 0; n < 2; ++n) { const size_t o = off + bj * HALF + n * 16; const u32x2v xw = *(const u32x2v*)(XR + o); f32x4 a = acc[ai][bj][m][n];
;                         const f32x4 xv = (f32x4){__uint_as_float(xw.x << 16), __uint_as_float(xw.x & 0xffff0000u), __uint_as_float(xw.y << 16), __uint_as_float(xw.y & 0xffff0000u)};
;                         if (MODE == 1) { const u32x2v pw = *(const u32x2v*)(PP + o); const f32x4 pv = (f32x4){__uint_as_float(pw.x << 16), __uint_as_float(pw.x & 0xffff0000u), __uint_as_float(pw.y << 16), __uint_as_float(pw.y & 0xffff0000u)};
; #pragma unroll
;                             for (int j = 0; j < 4; ++j) a[j] = pv[j] / (1.0f + __expf(-a[j])); }
;                         acc[ai][bj][m][n] = xv * DN_ALPHA + a; }
	v_lshlrev_b32_e32 v134, 16, v136
	s_nop 0
	v_mul_f32_e32 v71, v132, v138
	v_rcp_f32_e32 v132, v70
	v_and_b32_e32 v135, 0xffff0000, v136
	v_lshlrev_b32_e32 v136, 16, v137
	v_and_b32_e32 v137, 0xffff0000, v137
	s_nop 0
	v_mul_f32_e32 v70, v131, v132
	v_and_b32_e32 v132, 0xffff0000, v133
	v_lshlrev_b32_e32 v131, 16, v133
	v_rcp_f32_e32 v133, v73
	v_pk_fma_f32 v[70:71], v[134:135], s[2:3], v[70:71] op_sel_hi:[1,0,1]
	s_nop 0
	v_mul_f32_e32 v73, v132, v133
	v_rcp_f32_e32 v132, v72
	s_nop 0
	s_nop 0
	v_mul_f32_e32 v72, v131, v132
	v_add_u32_e32 v132, 0xa0, v130
	v_ashrrev_i32_e32 v133, 31, v132
	v_lshlrev_b64 v[132:133], 10, v[132:133]
	v_lshl_add_u64 v[132:133], v[132:133], 0, v[162:163]
	v_pk_fma_f32 v[72:73], v[136:137], s[2:3], v[72:73] op_sel_hi:[1,0,1]
	v_lshlrev_b64 v[132:133], 1, v[132:133]
	v_lshl_add_u64 v[134:135], s[50:51], 0, v[132:133]
	v_lshl_add_u64 v[132:133], s[52:53], 0, v[132:133]
	global_load_dwordx2 v[142:143], v[132:133], off
	global_load_dwordx2 v[136:137], v[134:135], off
	v_add_u32_e32 v130, 0xb0, v130
	s_waitcnt vmcnt(1)
	v_lshlrev_b32_e32 v131, 16, v142
	v_and_b32_e32 v142, 0xffff0000, v142
	v_rcp_f32_e32 v144, v67
	s_waitcnt vmcnt(0)
	v_lshlrev_b32_e32 v138, 16, v136
	v_and_b32_e32 v139, 0xffff0000, v136
	v_lshlrev_b32_e32 v136, 16, v137
	s_nop 0
	v_mul_f32_e32 v67, v142, v144
	v_rcp_f32_e32 v142, v66
	v_and_b32_e32 v137, 0xffff0000, v137
	s_nop 0
	v_mul_f32_e32 v66, v131, v142
	v_and_b32_e32 v142, 0xffff0000, v143
	v_lshlrev_b32_e32 v131, 16, v143
	v_rcp_f32_e32 v143, v69
	v_pk_fma_f32 v[66:67], v[138:139], s[2:3], v[66:67] op_sel_hi:[1,0,1]
	s_nop 0
	v_mul_f32_e32 v69, v142, v143
	v_rcp_f32_e32 v142, v68
	s_nop 0
	s_nop 0
	v_mul_f32_e32 v68, v131, v142
	global_load_dwordx2 v[142:143], v[132:133], off offset:32
	v_pk_fma_f32 v[68:69], v[136:137], s[2:3], v[68:69] op_sel_hi:[1,0,1]
	global_load_dwordx2 v[136:137], v[134:135], off offset:32
	s_waitcnt vmcnt(1)
	v_lshlrev_b32_e32 v131, 16, v142
	v_and_b32_e32 v142, 0xffff0000, v142
	v_rcp_f32_e32 v144, v55
	s_waitcnt vmcnt(0)
	v_lshlrev_b32_e32 v138, 16, v136
	v_and_b32_e32 v139, 0xffff0000, v136
	v_lshlrev_b32_e32 v136, 16, v137
	s_nop 0
	v_mul_f32_e32 v55, v142, v144
	v_rcp_f32_e32 v142, v54
	v_and_b32_e32 v137, 0xffff0000, v137
	s_nop 0
	v_mul_f32_e32 v54, v131, v142
	v_and_b32_e32 v142, 0xffff0000, v143
	v_lshlrev_b32_e32 v131, 16, v143
	v_rcp_f32_e32 v143, v57
	v_pk_fma_f32 v[54:55], v[138:139], s[2:3], v[54:55] op_sel_hi:[1,0,1]
	s_nop 0
	v_mul_f32_e32 v57, v142, v143
	v_rcp_f32_e32 v142, v56
	s_nop 0
	s_nop 0
	v_mul_f32_e32 v56, v131, v142
	global_load_dwordx2 v[142:143], v[132:133], off offset:256
	v_pk_fma_f32 v[56:57], v[136:137], s[2:3], v[56:57] op_sel_hi:[1,0,1]
	global_load_dwordx2 v[136:137], v[134:135], off offset:256
	s_waitcnt vmcnt(1)
	v_lshlrev_b32_e32 v131, 16, v142
	global_load_dwordx2 v[132:133], v[132:133], off offset:288
	v_and_b32_e32 v142, 0xffff0000, v142
	v_rcp_f32_e32 v144, v51
	s_waitcnt vmcnt(1)
	v_lshlrev_b32_e32 v138, 16, v136
	v_and_b32_e32 v139, 0xffff0000, v136
	v_lshlrev_b32_e32 v136, 16, v137
	s_nop 0
	v_mul_f32_e32 v51, v142, v144
	v_rcp_f32_e32 v142, v50
	v_and_b32_e32 v137, 0xffff0000, v137
	s_nop 0
	v_mul_f32_e32 v50, v131, v142
	v_and_b32_e32 v142, 0xffff0000, v143
	v_lshlrev_b32_e32 v131, 16, v143
	v_rcp_f32_e32 v143, v53
	v_pk_fma_f32 v[50:51], v[138:139], s[2:3], v[50:51] op_sel_hi:[1,0,1]
	s_nop 0
	v_mul_f32_e32 v53, v142, v143
	v_rcp_f32_e32 v142, v52
	s_nop 0
	s_nop 0
	v_mul_f32_e32 v52, v131, v142
	v_pk_fma_f32 v[52:53], v[136:137], s[2:3], v[52:53] op_sel_hi:[1,0,1]
	global_load_dwordx2 v[136:137], v[134:135], off offset:288
	s_waitcnt vmcnt(1)
	v_lshlrev_b32_e32 v131, 16, v132
	v_and_b32_e32 v132, 0xffff0000, v132
	v_rcp_f32_e32 v138, v31
	s_waitcnt vmcnt(0)
	v_lshlrev_b32_e32 v134, 16, v136
	s_nop 0
	v_mul_f32_e32 v31, v132, v138
	v_rcp_f32_e32 v132, v30
	v_and_b32_e32 v135, 0xffff0000, v136
	v_lshlrev_b32_e32 v136, 16, v137
	v_and_b32_e32 v137, 0xffff0000, v137
	s_nop 0
	v_mul_f32_e32 v30, v131, v132
	v_and_b32_e32 v132, 0xffff0000, v133
	v_lshlrev_b32_e32 v131, 16, v133
	v_rcp_f32_e32 v133, v33
	v_pk_fma_f32 v[30:31], v[134:135], s[2:3], v[30:31] op_sel_hi:[1,0,1]
	s_nop 0
	v_mul_f32_e32 v33, v132, v133
	v_rcp_f32_e32 v132, v32
	s_nop 0
	s_nop 0
	v_mul_f32_e32 v32, v131, v132
	v_ashrrev_i32_e32 v131, 31, v130
	v_lshlrev_b64 v[130:131], 10, v[130:131]
	v_lshl_add_u64 v[130:131], v[130:131], 0, v[162:163]
	v_lshlrev_b64 v[130:131], 1, v[130:131]
	v_pk_fma_f32 v[32:33], v[136:137], s[2:3], v[32:33] op_sel_hi:[1,0,1]
	v_lshl_add_u64 v[132:133], s[50:51], 0, v[130:131]
	v_lshl_add_u64 v[130:131], s[52:53], 0, v[130:131]
	global_load_dwordx2 v[138:139], v[130:131], off
	global_load_dwordx2 v[134:135], v[132:133], off
	s_waitcnt vmcnt(1)
	v_lshlrev_b32_e32 v142, 16, v138
	v_and_b32_e32 v138, 0xffff0000, v138
	v_rcp_f32_e32 v143, v27
	s_waitcnt vmcnt(0)
	v_lshlrev_b32_e32 v136, 16, v134
	v_and_b32_e32 v137, 0xffff0000, v134
	v_lshlrev_b32_e32 v134, 16, v135
	s_nop 0
	v_mul_f32_e32 v27, v138, v143
	v_rcp_f32_e32 v138, v26
	v_and_b32_e32 v135, 0xffff0000, v135
	s_nop 0
	v_mul_f32_e32 v26, v142, v138
	v_lshlrev_b32_e32 v138, 16, v139
	v_and_b32_e32 v139, 0xffff0000, v139
	v_rcp_f32_e32 v142, v29
	v_pk_fma_f32 v[26:27], v[136:137], s[2:3], v[26:27] op_sel_hi:[1,0,1]
	s_nop 0
	v_mul_f32_e32 v29, v139, v142
	v_rcp_f32_e32 v139, v28
	s_nop 0
	s_nop 0
	v_mul_f32_e32 v28, v138, v139
	global_load_dwordx2 v[138:139], v[130:131], off offset:32
	v_pk_fma_f32 v[28:29], v[134:135], s[2:3], v[28:29] op_sel_hi:[1,0,1]
	global_load_dwordx2 v[134:135], v[132:133], off offset:32
	s_waitcnt vmcnt(1)
;     __device__ __forceinline__ bool run(const f32x4 (&v)[2][2][4][2], const Unit& u, int wr, int wc, int fr, int fq, PG8_LAS unsigned char* lds, int wid, int lane) const {
;     ...
;                 float s = 0.f;
; #pragma unroll
;                 for (int bj = 0; bj < 2; ++bj)
; #pragma unroll
;                     for (int n = 0; n < 2; ++n) { const f32x4 x = v[ai][bj][m][n]; s += (x[0] + x[1]) + (x[2] + x[3]); }
;                 s += __shfl_xor(s, 16); s += __shfl_xor(s, 32);
;                 const float mw = s * (1.0f / 64.0f); float q = 0.f;
; #pragma unroll
;                 for (int bj = 0; bj < 2; ++bj)
; #pragma unroll
;                     for (int n = 0; n < 2; ++n) { const f32x4 d = v[ai][bj][m][n] - mw; q += (d[0] * d[0] + d[1] * d[1]) + (d[2] * d[2] + d[3] * d[3]); }
;                 q += __shfl_xor(q, 16); q += __shfl_xor(q, 32);
;                 if (fq == 0) P[(ai * HALF + wr * 64 + m * 16 + fr) * 4 + wc] = (f32x2v){mw, q};
;     __device__ __forceinline__ void fused(f32x4 (&acc)[2][2][4][2], const Unit& u, int wr, int wc, int fr, int fq, PG8_LAS unsigned char* lds, int wid, int lane) const {
;     ...
;                     for (int n = 0; n < 2; ++n) { const size_t o = off + bj * HALF + n * 16; const u32x2v xw = *(const u32x2v*)(XR + o); f32x4 a = acc[ai][bj][m][n];
;                         const f32x4 xv = (f32x4){__uint_as_float(xw.x << 16), __uint_as_float(xw.x & 0xffff0000u), __uint_as_float(xw.y << 16), __uint_as_float(xw.y & 0xffff0000u)};
;                         if (MODE == 1) { const u32x2v pw = *(const u32x2v*)(PP + o); const f32x4 pv = (f32x4){__uint_as_float(pw.x << 16), __uint_as_float(pw.x & 0xffff0000u), __uint_as_float(pw.y << 16), __uint_as_float(pw.y & 0xffff0000u)};
; #pragma unroll
;                             for (int j = 0; j < 4; ++j) a[j] = pv[j] / (1.0f + __expf(-a[j])); }
;                         acc[ai][bj][m][n] = xv * DN_ALPHA + a; }
	v_lshlrev_b32_e32 v142, 16, v138
	v_and_b32_e32 v138, 0xffff0000, v138
	v_rcp_f32_e32 v143, v23
	s_waitcnt vmcnt(0)
	v_lshlrev_b32_e32 v136, 16, v134
	v_and_b32_e32 v137, 0xffff0000, v134
	v_lshlrev_b32_e32 v134, 16, v135
	s_nop 0
	v_mul_f32_e32 v23, v138, v143
	v_rcp_f32_e32 v138, v22
	v_and_b32_e32 v135, 0xffff0000, v135
	s_nop 0
	v_mul_f32_e32 v22, v142, v138
	v_lshlrev_b32_e32 v138, 16, v139
	v_and_b32_e32 v139, 0xffff0000, v139
	v_rcp_f32_e32 v142, v25
	v_pk_fma_f32 v[22:23], v[136:137], s[2:3], v[22:23] op_sel_hi:[1,0,1]
	s_nop 0
	v_mul_f32_e32 v25, v139, v142
	v_rcp_f32_e32 v139, v24
	s_nop 0
	s_nop 0
	v_mul_f32_e32 v24, v138, v139
	global_load_dwordx2 v[138:139], v[130:131], off offset:256
	v_pk_fma_f32 v[24:25], v[134:135], s[2:3], v[24:25] op_sel_hi:[1,0,1]
	global_load_dwordx2 v[134:135], v[132:133], off offset:256
	s_waitcnt vmcnt(1)
	v_lshlrev_b32_e32 v142, 16, v138
	v_and_b32_e32 v138, 0xffff0000, v138
	global_load_dwordx2 v[130:131], v[130:131], off offset:288
	v_rcp_f32_e32 v143, v19
	s_waitcnt vmcnt(1)
	v_lshlrev_b32_e32 v136, 16, v134
	v_and_b32_e32 v137, 0xffff0000, v134
	v_lshlrev_b32_e32 v134, 16, v135
	s_nop 0
	v_mul_f32_e32 v19, v138, v143
	v_rcp_f32_e32 v138, v18
	v_and_b32_e32 v135, 0xffff0000, v135
	s_nop 0
	v_mul_f32_e32 v18, v142, v138
	v_lshlrev_b32_e32 v138, 16, v139
	v_and_b32_e32 v139, 0xffff0000, v139
	v_rcp_f32_e32 v142, v21
	v_pk_fma_f32 v[18:19], v[136:137], s[2:3], v[18:19] op_sel_hi:[1,0,1]
	s_nop 0
	v_mul_f32_e32 v21, v139, v142
	v_rcp_f32_e32 v139, v20
	s_waitcnt vmcnt(0)
	v_lshlrev_b32_e32 v136, 16, v130
	s_nop 0
	v_mul_f32_e32 v20, v138, v139
	v_pk_fma_f32 v[20:21], v[134:135], s[2:3], v[20:21] op_sel_hi:[1,0,1]
	global_load_dwordx2 v[134:135], v[132:133], off offset:288
	v_and_b32_e32 v130, 0xffff0000, v130
	v_rcp_f32_e32 v137, v3
	s_waitcnt vmcnt(0)
	v_lshlrev_b32_e32 v132, 16, v134
	s_nop 0
	v_mul_f32_e32 v3, v130, v137
	v_rcp_f32_e32 v130, v2
	v_and_b32_e32 v133, 0xffff0000, v134
	v_lshlrev_b32_e32 v134, 16, v135
	v_and_b32_e32 v135, 0xffff0000, v135
	s_nop 0
	v_mul_f32_e32 v2, v136, v130
	v_lshlrev_b32_e32 v130, 16, v131
	v_and_b32_e32 v131, 0xffff0000, v131
	v_rcp_f32_e32 v136, v5
	v_pk_fma_f32 v[2:3], v[132:133], s[2:3], v[2:3] op_sel_hi:[1,0,1]
	v_xor_b32_e32 v132, 32, v223
	v_mov_b32_e32 v133, v8
	s_nop 0
	v_mul_f32_e32 v5, v131, v136
	v_rcp_f32_e32 v131, v4
	v_readlane_b32 s0, v255, 10
	s_nop 0
	v_mul_f32_e32 v4, v130, v131
	v_and_b32_e32 v131, 64, v223
	v_xor_b32_e32 v130, 16, v223
	v_add_u32_e32 v131, 64, v131
	v_cmp_lt_i32_e32 vcc, v130, v131
	v_pk_fma_f32 v[4:5], v[134:135], s[2:3], v[4:5] op_sel_hi:[1,0,1]
	v_mov_b32_e32 v134, v6
	v_cndmask_b32_e32 v130, v223, v130, vcc
	v_cmp_lt_i32_e32 vcc, v132, v131
	v_mov_b32_e32 v135, v9
	v_mov_b32_e32 v136, v10
	v_cndmask_b32_e32 v131, v223, v132, vcc
	v_mov_b32_e32 v132, v7
	v_pk_add_f32 v[132:133], v[132:133], v[134:135]
	v_mov_b32_e32 v134, v11
	v_mov_b32_e32 v135, v12
	v_mov_b32_e32 v137, v13
	v_pk_add_f32 v[134:135], v[134:135], v[136:137]
	v_add_f32_e32 v132, v132, v133
	v_pk_add_f32 v[134:135], v[134:135], v[134:135] op_sel_hi:[0,1]
	v_add_f32_e32 v133, 0, v132
	v_add_f32_e32 v137, v14, v15
	v_add_f32_e32 v139, v16, v17
	v_mov_b32_e32 v136, v34
	v_mov_b32_e32 v138, v35
	v_mov_b32_e32 v134, v36
	v_mov_b32_e32 v132, v37
	v_pk_add_f32 v[136:137], v[136:137], v[138:139]
	v_pk_add_f32 v[132:133], v[134:135], v[132:133]
	v_lshlrev_b32_e32 v130, 2, v130
	v_pk_add_f32 v[132:133], v[136:137], v[132:133]
	v_lshlrev_b32_e32 v131, 2, v131
	v_add_f32_e32 v132, v132, v133
	ds_bpermute_b32 v133, v130, v132
	v_cmp_gt_u32_e32 vcc, 16, v0
	s_waitcnt lgkmcnt(0)
	v_add_f32_e32 v132, v132, v133
	ds_bpermute_b32 v133, v131, v132
	s_waitcnt lgkmcnt(0)
	v_add_f32_e32 v133, v132, v133
	v_fmamk_f32 v134, v133, 0xbc800000, v9
	v_fmamk_f32 v136, v133, 0xbc800000, v7
	v_fmamk_f32 v132, v133, 0xbc800000, v8
	v_fmamk_f32 v135, v133, 0xbc800000, v6
	v_mul_f32_e32 v136, v136, v136
	v_mul_f32_e32 v134, v134, v134
	v_fmac_f32_e32 v136, v135, v135
	v_fmac_f32_e32 v134, v132, v132
	v_fmamk_f32 v135, v133, 0xbc800000, v13
	v_fmamk_f32 v137, v133, 0xbc800000, v11
	v_add_f32_e32 v132, v136, v134
	v_fmamk_f32 v134, v133, 0xbc800000, v12
	v_fmamk_f32 v136, v133, 0xbc800000, v10
	v_mul_f32_e32 v137, v137, v137
	v_mul_f32_e32 v135, v135, v135
	v_fmac_f32_e32 v137, v136, v136
	v_fmac_f32_e32 v135, v134, v134
	v_add_f32_e32 v134, v137, v135
	v_fmamk_f32 v135, v133, 0xbc800000, v17
	v_fmamk_f32 v137, v133, 0xbc800000, v15
	v_add_f32_e32 v132, v132, v134
	v_fmamk_f32 v134, v133, 0xbc800000, v16
	v_fmamk_f32 v136, v133, 0xbc800000, v14
	v_mul_f32_e32 v137, v137, v137
	v_mul_f32_e32 v135, v135, v135
	v_fmac_f32_e32 v137, v136, v136
	v_fmac_f32_e32 v135, v134, v134
	v_add_f32_e32 v134, v137, v135
	v_fmamk_f32 v135, v133, 0xbc800000, v37
	v_fmamk_f32 v137, v133, 0xbc800000, v35
	v_add_f32_e32 v132, v134, v132
	v_fmamk_f32 v134, v133, 0xbc800000, v36
	v_fmamk_f32 v136, v133, 0xbc800000, v34
	v_mul_f32_e32 v137, v137, v137
	v_mul_f32_e32 v135, v135, v135
	v_fmac_f32_e32 v137, v136, v136
	v_fmac_f32_e32 v135, v134, v134
	v_add_f32_e32 v134, v137, v135
	v_add_f32_e32 v132, v134, v132
	ds_bpermute_b32 v134, v130, v132
	s_waitcnt lgkmcnt(0)
	v_add_f32_e32 v134, v132, v134
	ds_bpermute_b32 v135, v131, v134
	v_lshl_add_u32 v132, v141, 5, s0
	s_and_saveexec_b64 s[2:3], vcc
	s_cbranch_execz .LBB0_2315
	v_mul_f32_e32 v136, 0x3c800000, v133
	s_waitcnt lgkmcnt(0)
	v_add_f32_e32 v137, v134, v135
	ds_write_b64 v132, v[136:137] offset:1024
